# attention K/V tiles staged by LDS-DMA (source-side swizzle) instead of VGPR + ds_write; K issued after QKt, V after the PV barrier
# speedup vs baseline: 1.0106x; 1.0059x over previous
; __device__ __forceinline__ int opaque_tid() { int t = threadIdx.x; asm volatile("" : "+v"(t)); return t; }
; __device__ __forceinline__ void attn_dense_body(const bf16* Qb, const bf16* __restrict__ Kh, const bf16* __restrict__ Vh,
;                                                 bf16* Ob, int seq, char* lds, const float* __restrict__ qg, const float* __restrict__ rope, int s0) {
;   const int tid = opaque_tid(), wid = tid >> 6, lane = tid & 63, r32 = lane & 31, hi = lane >> 5;
;   bf16* V_lds = (bf16*)lds; bf16* K_lds = (bf16*)(lds + 2 * SHM_V);
;   float* ws = (float*)(lds + 2 * SHM_V + 2 * SHM_K) + wid * 64; float* li_l = ws; float* al_l = ws + 32;
; __global__ void __launch_bounds__(NTHR, 2) mega_fwd(Args a0) {
;     ...
;                 if (!PROBE || (PROBE & 2) || !dry) for (int it = bx; it < NB * 8 * 16; it += G) {
;                     const int b = it & 7, u = it >> 3, h = u >> 4, qb = u & 15;
;                     const size_t qoff = ((size_t)(b * SEQ + qb * 256)) * DM + h * 128, koff = (size_t)b * SEQ * 256 + (h >> 2) * 128;
;                     att::attn_dense_body(Qb + qoff, Kb + koff, Vb + koff, (dry ? H : Qb) + qoff, SEQ, (char*)lds_raw, a.in[I_QG] + l * 128, (const float*)(ws + WS_ROPE), qb * 256);
.LBB0_92:
	v_readlane_b32 s0, v253, 10
	v_readlane_b32 s1, v253, 11
	s_andn2_b64 vcc, exec, s[0:1]
	s_cbranch_vccnz .LBB0_119
	v_readlane_b32 s0, v255, 7
	v_readlane_b32 s1, v255, 8
	s_load_dwordx2 s[0:1], s[0:1], 0x40
	v_readlane_b32 s16, v255, 15
	v_readlane_b32 s17, v255, 16
	s_lshl_b32 s16, s16, 7
	s_ashr_i32 s17, s16, 31
	s_lshl_b64 s[16:17], s[16:17], 2
	s_waitcnt lgkmcnt(0)
	s_add_u32 s16, s0, s16
	s_addc_u32 s17, s1, s17
	s_add_u32 s54, s22, 0x200000
	s_addc_u32 s55, s23, 0
	v_readfirstlane_b32 s98, v196
	s_nop 3
	s_lshr_b32 s98, s98, 6
	s_lshl_b32 s98, s98, 11
	s_mov_b32 s19, s2
	s_branch .LBB0_95

; __device__ __forceinline__ void attn_dense_body(const bf16* Qb, const bf16* __restrict__ Kh, const bf16* __restrict__ Vh,
;                                                 bf16* Ob, int seq, char* lds, const float* __restrict__ qg, const float* __restrict__ rope, int s0) {
;     ...
;   const bf16* Qw = Qb + (long)(wid * QBLK + r32) * LDQ + hi * 8;
; #pragma unroll
;   for (int d0 = 0; d0 < 8; ++d0) qr[d0] = ld8(Qw + d0 * 16);
;   {
;     float ss = 0.f;
; #pragma unroll
;     for (int d0 = 0; d0 < 8; ++d0)
; #pragma unroll
;       for (int e = 0; e < 8; ++e) { const float x = __uint_as_float((unsigned)(unsigned short)qr[d0][e] << 16); ss += x * x; }
;     { auto rr = __builtin_amdgcn_permlane32_swap(__float_as_uint(ss), __float_as_uint(ss), false, false); ss = __uint_as_float(rr[0]) + __uint_as_float(rr[1]); }
;     const float rstd = rsqrtf(ss * (1.f / 128.f) + 1e-6f) * (SCALE * 1.4426950408889634f);
;     const float* rp = rope + (long)(s0 + wid * QBLK + r32) * 128 + hi * 8;
;     const float* gp = qg + hi * 8;
; #pragma unroll
;     for (int d0 = 0; d0 < 8; ++d0) {
;       const float4 g0 = *reinterpret_cast<const float4*>(gp + d0 * 16), g1 = *reinterpret_cast<const float4*>(gp + d0 * 16 + 4);
;       const float4 c0 = *reinterpret_cast<const float4*>(rp + d0 * 16), c1 = *reinterpret_cast<const float4*>(rp + d0 * 16 + 4);
.LBB0_95:
	s_lshl_b32 s0, s19, 5
	s_ashr_i32 s28, s19, 2
	s_and_b32 s25, s19, 7
	s_and_b32 s26, s0, 0xf00
	s_and_b32 s0, s19, 0xffffff80
	s_and_b32 s28, s28, 0xffffff80
	s_ashr_i32 s1, s0, 31
	s_lshl_b32 s27, s25, 20
	s_ashr_i32 s29, s28, 31
	s_add_u32 s52, s27, s28
	s_addc_u32 s53, 0, s29
	s_lshl_b32 s25, s25, 23
	s_lshl_b32 s27, s26, 11
	s_or_b32 s25, s27, s25
	v_readlane_b32 s28, v255, 21
	v_readlane_b32 s29, v255, 22
	s_add_u32 s25, s28, s25
	s_addc_u32 s27, s29, 0
	s_lshl_b64 s[0:1], s[0:1], 1
	v_mov_b32_e32 v29, v196
	s_add_u32 s60, s25, s0
	s_movk_i32 s0, 0xffe0
	v_ashrrev_i32_e32 v2, 1, v29
	v_bfi_b32 v0, s0, v2, v29
	v_ashrrev_i32_e32 v1, 31, v0
	s_addc_u32 s61, s27, s1
	v_bfe_u32 v145, v29, 5, 1
	v_lshlrev_b64 v[0:1], 11, v[0:1]
	v_lshl_add_u64 v[0:1], s[60:61], 0, v[0:1]
	v_lshlrev_b32_e32 v194, 4, v145
	v_mov_b32_e32 v195, v144
	v_lshl_add_u64 v[0:1], v[0:1], 0, v[194:195]
	global_load_dwordx4 v[12:15], v[0:1], off offset:224
	global_load_dwordx4 v[18:21], v[0:1], off offset:192
	global_load_dwordx4 v[30:33], v[0:1], off offset:160
	global_load_dwordx4 v[36:39], v[0:1], off offset:128
	global_load_dwordx4 v[44:47], v[0:1], off offset:96
	global_load_dwordx4 v[52:55], v[0:1], off offset:64
	global_load_dwordx4 v[56:59], v[0:1], off offset:32
	global_load_dwordx4 v[60:63], v[0:1], off
	v_and_b32_e32 v195, 31, v29
	v_and_b32_e32 v192, 0xffffffe0, v2
	v_or_b32_e32 v0, s26, v195
	v_add_u32_e32 v0, v0, v192
	v_ashrrev_i32_e32 v1, 31, v0
	v_lshlrev_b64 v[0:1], 9, v[0:1]
	v_mov_b32_e32 v9, v144
	v_and_b32_e32 v8, 32, v29
	v_lshl_add_u64 v[0:1], s[54:55], 0, v[0:1]
	v_lshl_add_u64 v[10:11], v[0:1], 0, v[8:9]
	s_lshl_b64 s[0:1], s[52:53], 1
	s_add_u32 s56, s36, s0
	s_addc_u32 s27, s37, s1
	v_readlane_b32 s28, v255, 23
	v_readlane_b32 s29, v255, 24
	s_add_u32 s88, s28, s0
	s_addc_u32 s0, s29, s1
	s_add_i32 s25, 0, 0x10000
	s_cmp_lg_u32 0, -1
	s_cselect_b32 s26, 0, 0
	s_and_b32 s89, s0, 0xffff
	s_mov_b32 s95, s87
	s_mov_b32 s92, s88
	s_mov_b32 s93, s89
	s_mov_b32 s58, s94
	s_mov_b32 s59, s87
	s_and_b32 s57, s27, 0xffff
	v_lshlrev_b32_e32 v120, 4, v29
	v_lshlrev_b32_e32 v116, 8, v195
	v_and_b32_e32 v117, 0x70, v120
	v_or_b32_e32 v118, 0xe0, v194
	v_and_b32_e32 v121, 63, v29
	v_lshlrev_b32_e32 v123, 1, v29
	v_cmp_gt_u32_e64 s[52:53], 32, v121
	s_mov_b32 s66, s65
	s_mov_b32 s67, s65
	s_mov_b32 s68, s65
	s_mov_b32 s69, s65
	s_mov_b32 s70, s65
	s_mov_b32 s71, s65
	s_mov_b32 s72, s65
	s_mov_b32 s73, s65
	s_mov_b32 s74, s65
	s_mov_b32 s75, s65
	s_mov_b32 s76, s65
	s_mov_b32 s77, s65
	s_mov_b32 s79, s65
	v_and_b32_e32 v122, 0x3fffffc0, v29
	v_lshl_add_u32 v210, v122, 2, s25
	s_mov_b32 s0, -1
	v_mov_b32_e32 v193, 0
	v_mov_b32_e32 v228, 1.0
	s_mov_b32 s1, 0x18000
	v_lshl_add_u32 v211, v195, 2, v210
	s_waitcnt vmcnt(7)
	v_and_b32_e32 v1, 0xffff0000, v15
	v_lshlrev_b32_e32 v0, 16, v15
	v_and_b32_e32 v3, 0xffff0000, v14
	v_lshlrev_b32_e32 v2, 16, v14
	v_and_b32_e32 v5, 0xffff0000, v13
	v_lshlrev_b32_e32 v4, 16, v13
	v_and_b32_e32 v7, 0xffff0000, v12
	v_lshlrev_b32_e32 v6, 16, v12
	s_waitcnt vmcnt(6)
	v_and_b32_e32 v13, 0xffff0000, v21
	v_lshlrev_b32_e32 v12, 16, v21
	v_and_b32_e32 v15, 0xffff0000, v20
	v_lshlrev_b32_e32 v14, 16, v20
	s_waitcnt vmcnt(5)
	v_and_b32_e32 v21, 0xffff0000, v33
	v_lshlrev_b32_e32 v20, 16, v33
	v_and_b32_e32 v23, 0xffff0000, v32
	v_lshlrev_b32_e32 v22, 16, v32
	v_and_b32_e32 v25, 0xffff0000, v31
	v_lshlrev_b32_e32 v24, 16, v31
	v_and_b32_e32 v27, 0xffff0000, v30
	v_lshlrev_b32_e32 v26, 16, v30
	s_waitcnt vmcnt(4)
	v_and_b32_e32 v31, 0xffff0000, v39
	v_lshlrev_b32_e32 v30, 16, v39
	v_and_b32_e32 v33, 0xffff0000, v38
	v_lshlrev_b32_e32 v32, 16, v38
	s_waitcnt vmcnt(3)
	v_and_b32_e32 v39, 0xffff0000, v47
	v_lshlrev_b32_e32 v38, 16, v47
	v_and_b32_e32 v41, 0xffff0000, v46
	v_lshlrev_b32_e32 v40, 16, v46
	s_waitcnt vmcnt(2)
	v_and_b32_e32 v47, 0xffff0000, v55
	v_lshlrev_b32_e32 v46, 16, v55
	v_and_b32_e32 v49, 0xffff0000, v54
	v_lshlrev_b32_e32 v48, 16, v54
	s_waitcnt vmcnt(1)
	v_and_b32_e32 v81, 0xffff0000, v57
	v_lshlrev_b32_e32 v80, 16, v57
	v_and_b32_e32 v83, 0xffff0000, v56
	v_lshlrev_b32_e32 v82, 16, v56
	global_load_dwordx4 v[54:57], v8, s[16:17] offset:16
	global_load_dwordx4 v[64:67], v8, s[16:17]
	global_load_dwordx4 v[68:71], v[10:11], off offset:16
	global_load_dwordx4 v[72:75], v[10:11], off
	global_load_dwordx4 v[96:99], v8, s[16:17] offset:64
	global_load_dwordx4 v[100:103], v[10:11], off offset:64
	global_load_dwordx4 v[104:107], v8, s[16:17] offset:80
	global_load_dwordx4 v[108:111], v[10:11], off offset:80
	global_load_dwordx4 v[124:127], v8, s[16:17] offset:128
	global_load_dwordx4 v[128:131], v8, s[16:17] offset:144
	global_load_dwordx4 v[132:135], v[10:11], off offset:128
	global_load_dwordx4 v[136:139], v[10:11], off offset:144
	global_load_dwordx4 v[88:91], v8, s[16:17] offset:192
	global_load_dwordx4 v[92:95], v8, s[16:17] offset:208
	global_load_dwordx4 v[112:115], v[10:11], off offset:192
	global_load_dwordx4 v[140:143], v[10:11], off offset:208
	global_load_dwordx4 v[178:181], v8, s[16:17] offset:256
	global_load_dwordx4 v[182:185], v8, s[16:17] offset:272
	global_load_dwordx4 v[186:189], v[10:11], off offset:256
	global_load_dwordx4 v[242:245], v[10:11], off offset:272
	s_waitcnt vmcnt(20)
; __device__ __forceinline__ void attn_dense_body(const bf16* Qb, const bf16* __restrict__ Kh, const bf16* __restrict__ Vh,
;                                                 bf16* Ob, int seq, char* lds, const float* __restrict__ qg, const float* __restrict__ rope, int s0) {
;     ...
;     float ss = 0.f;
; #pragma unroll
;     for (int d0 = 0; d0 < 8; ++d0)
; #pragma unroll
;       for (int e = 0; e < 8; ++e) { const float x = __uint_as_float((unsigned)(unsigned short)qr[d0][e] << 16); ss += x * x; }
;     { auto rr = __builtin_amdgcn_permlane32_swap(__float_as_uint(ss), __float_as_uint(ss), false, false); ss = __uint_as_float(rr[0]) + __uint_as_float(rr[1]); }
;     const float rstd = rsqrtf(ss * (1.f / 128.f) + 1e-6f) * (SCALE * 1.4426950408889634f);
;     const float* rp = rope + (long)(s0 + wid * QBLK + r32) * 128 + hi * 8;
;     const float* gp = qg + hi * 8;
; #pragma unroll
;     for (int d0 = 0; d0 < 8; ++d0) {
;       const float4 g0 = *reinterpret_cast<const float4*>(gp + d0 * 16), g1 = *reinterpret_cast<const float4*>(gp + d0 * 16 + 4);
;       const float4 c0 = *reinterpret_cast<const float4*>(rp + d0 * 16), c1 = *reinterpret_cast<const float4*>(rp + d0 * 16 + 4);
;       const float gg[8] = {g0.x, g0.y, g0.z, g0.w, g1.x, g1.y, g1.z, g1.w};
;       const float cs[8] = {c0.x, c0.y, c0.z, c0.w, c1.x, c1.y, c1.z, c1.w};
;       unsigned w[4];
; #pragma unroll
;       for (int p = 0; p < 4; ++p) {
;         const float y0 = __uint_as_float((unsigned)(unsigned short)qr[d0][2 * p] << 16) * rstd * gg[2 * p], y1 = __uint_as_float((unsigned)(unsigned short)qr[d0][2 * p + 1] << 16) * rstd * gg[2 * p + 1];
	v_and_b32_e32 v85, 0xffff0000, v61
	v_lshlrev_b32_e32 v84, 16, v61
	v_and_b32_e32 v61, 0xffff0000, v60
	v_lshlrev_b32_e32 v60, 16, v60
	v_mul_f32_e32 v28, v61, v61
	v_pk_fma_f32 v[86:87], v[60:61], v[60:61], v[28:29] op_sel_hi:[1,1,0]
	v_mul_f32_e32 v28, v85, v85
	v_pk_fma_f32 v[86:87], v[84:85], v[84:85], v[86:87]
	v_and_b32_e32 v77, 0xffff0000, v59
	v_lshlrev_b32_e32 v76, 16, v59
	v_and_b32_e32 v79, 0xffff0000, v58
	v_lshlrev_b32_e32 v78, 16, v58
	v_and_b32_e32 v59, 0xffff0000, v63
	v_lshlrev_b32_e32 v58, 16, v63
	v_and_b32_e32 v63, 0xffff0000, v62
	v_lshlrev_b32_e32 v62, 16, v62
	v_pk_add_f32 v[86:87], v[28:29], v[86:87] op_sel_hi:[0,1]
	v_pk_fma_f32 v[86:87], v[62:63], v[62:63], v[86:87]
	v_mul_f32_e32 v28, v63, v63
	v_pk_add_f32 v[86:87], v[28:29], v[86:87] op_sel_hi:[0,1]
	v_pk_fma_f32 v[86:87], v[58:59], v[58:59], v[86:87]
	v_mul_f32_e32 v28, v59, v59
	v_pk_add_f32 v[86:87], v[28:29], v[86:87] op_sel_hi:[0,1]
	v_pk_fma_f32 v[86:87], v[82:83], v[82:83], v[86:87]
	v_mul_f32_e32 v28, v83, v83
	v_pk_add_f32 v[86:87], v[28:29], v[86:87] op_sel_hi:[0,1]
	v_pk_fma_f32 v[86:87], v[80:81], v[80:81], v[86:87]
	v_mul_f32_e32 v28, v81, v81
	v_pk_add_f32 v[86:87], v[28:29], v[86:87] op_sel_hi:[0,1]
	v_pk_fma_f32 v[86:87], v[78:79], v[78:79], v[86:87]
	v_mul_f32_e32 v28, v79, v79
	v_pk_add_f32 v[86:87], v[28:29], v[86:87] op_sel_hi:[0,1]
	v_pk_fma_f32 v[86:87], v[76:77], v[76:77], v[86:87]
	v_mul_f32_e32 v28, v77, v77
	v_and_b32_e32 v51, 0xffff0000, v53
	v_lshlrev_b32_e32 v50, 16, v53
	v_and_b32_e32 v53, 0xffff0000, v52
	v_lshlrev_b32_e32 v52, 16, v52
	v_pk_add_f32 v[86:87], v[28:29], v[86:87] op_sel_hi:[0,1]
	v_pk_fma_f32 v[86:87], v[52:53], v[52:53], v[86:87]
	v_mul_f32_e32 v28, v53, v53
	v_pk_add_f32 v[86:87], v[28:29], v[86:87] op_sel_hi:[0,1]
	v_pk_fma_f32 v[86:87], v[50:51], v[50:51], v[86:87]
	v_mul_f32_e32 v28, v51, v51
	v_pk_add_f32 v[86:87], v[28:29], v[86:87] op_sel_hi:[0,1]
	v_pk_fma_f32 v[86:87], v[48:49], v[48:49], v[86:87]
	v_mul_f32_e32 v28, v49, v49
	v_pk_add_f32 v[86:87], v[28:29], v[86:87] op_sel_hi:[0,1]
	v_pk_fma_f32 v[86:87], v[46:47], v[46:47], v[86:87]
	v_mul_f32_e32 v28, v47, v47
	v_and_b32_e32 v43, 0xffff0000, v45
	v_lshlrev_b32_e32 v42, 16, v45
	v_and_b32_e32 v45, 0xffff0000, v44
	v_lshlrev_b32_e32 v44, 16, v44
	v_pk_add_f32 v[86:87], v[28:29], v[86:87] op_sel_hi:[0,1]
	v_pk_fma_f32 v[86:87], v[44:45], v[44:45], v[86:87]
	v_mul_f32_e32 v28, v45, v45
	v_pk_add_f32 v[86:87], v[28:29], v[86:87] op_sel_hi:[0,1]
	v_pk_fma_f32 v[86:87], v[42:43], v[42:43], v[86:87]
	v_mul_f32_e32 v28, v43, v43
	v_pk_add_f32 v[86:87], v[28:29], v[86:87] op_sel_hi:[0,1]
	v_pk_fma_f32 v[86:87], v[40:41], v[40:41], v[86:87]
	v_mul_f32_e32 v28, v41, v41
	v_pk_add_f32 v[86:87], v[28:29], v[86:87] op_sel_hi:[0,1]
	v_pk_fma_f32 v[86:87], v[38:39], v[38:39], v[86:87]
	v_mul_f32_e32 v28, v39, v39
	v_and_b32_e32 v35, 0xffff0000, v37
	v_lshlrev_b32_e32 v34, 16, v37
	v_and_b32_e32 v37, 0xffff0000, v36
	v_lshlrev_b32_e32 v36, 16, v36
	v_pk_add_f32 v[86:87], v[28:29], v[86:87] op_sel_hi:[0,1]
	v_pk_fma_f32 v[86:87], v[36:37], v[36:37], v[86:87]
	v_mul_f32_e32 v28, v37, v37
	v_pk_add_f32 v[86:87], v[28:29], v[86:87] op_sel_hi:[0,1]
	v_pk_fma_f32 v[86:87], v[34:35], v[34:35], v[86:87]
	v_mul_f32_e32 v28, v35, v35
	v_pk_add_f32 v[86:87], v[28:29], v[86:87] op_sel_hi:[0,1]
	v_pk_fma_f32 v[86:87], v[32:33], v[32:33], v[86:87]
	v_mul_f32_e32 v28, v33, v33
	v_pk_add_f32 v[86:87], v[28:29], v[86:87] op_sel_hi:[0,1]
	v_pk_fma_f32 v[86:87], v[30:31], v[30:31], v[86:87]
	v_mul_f32_e32 v28, v31, v31
	v_pk_add_f32 v[86:87], v[28:29], v[86:87] op_sel_hi:[0,1]
	v_pk_fma_f32 v[86:87], v[26:27], v[26:27], v[86:87]
	v_mul_f32_e32 v28, v27, v27
	v_pk_add_f32 v[86:87], v[28:29], v[86:87] op_sel_hi:[0,1]
	v_pk_fma_f32 v[86:87], v[24:25], v[24:25], v[86:87]
	v_mul_f32_e32 v28, v25, v25
	v_pk_add_f32 v[86:87], v[28:29], v[86:87] op_sel_hi:[0,1]
	v_pk_fma_f32 v[86:87], v[22:23], v[22:23], v[86:87]
	v_mul_f32_e32 v28, v23, v23
	v_pk_add_f32 v[86:87], v[28:29], v[86:87] op_sel_hi:[0,1]
	v_pk_fma_f32 v[86:87], v[20:21], v[20:21], v[86:87]
	v_mul_f32_e32 v28, v21, v21
	v_and_b32_e32 v17, 0xffff0000, v19
	v_lshlrev_b32_e32 v16, 16, v19
	v_and_b32_e32 v19, 0xffff0000, v18
	v_lshlrev_b32_e32 v18, 16, v18
	v_pk_add_f32 v[86:87], v[28:29], v[86:87] op_sel_hi:[0,1]
	v_pk_fma_f32 v[86:87], v[18:19], v[18:19], v[86:87]
	v_mul_f32_e32 v28, v19, v19
	v_pk_add_f32 v[86:87], v[28:29], v[86:87] op_sel_hi:[0,1]
	v_pk_fma_f32 v[86:87], v[16:17], v[16:17], v[86:87]
	v_mul_f32_e32 v28, v17, v17
	v_pk_add_f32 v[86:87], v[28:29], v[86:87] op_sel_hi:[0,1]
	v_pk_fma_f32 v[86:87], v[14:15], v[14:15], v[86:87]
	v_mul_f32_e32 v28, v15, v15
	v_pk_add_f32 v[86:87], v[28:29], v[86:87] op_sel_hi:[0,1]
	v_pk_fma_f32 v[86:87], v[12:13], v[12:13], v[86:87]
	v_mul_f32_e32 v28, v13, v13
	v_pk_add_f32 v[86:87], v[28:29], v[86:87] op_sel_hi:[0,1]
	v_pk_fma_f32 v[86:87], v[6:7], v[6:7], v[86:87]
	v_mul_f32_e32 v28, v7, v7
	v_pk_add_f32 v[86:87], v[28:29], v[86:87] op_sel_hi:[0,1]
	v_pk_fma_f32 v[86:87], v[4:5], v[4:5], v[86:87]
	v_mul_f32_e32 v28, v5, v5
	v_pk_add_f32 v[86:87], v[28:29], v[86:87] op_sel_hi:[0,1]
	v_pk_fma_f32 v[86:87], v[2:3], v[2:3], v[86:87]
	v_mul_f32_e32 v28, v3, v3
	v_pk_add_f32 v[86:87], v[28:29], v[86:87] op_sel_hi:[0,1]
	v_pk_fma_f32 v[86:87], v[0:1], v[0:1], v[86:87]
	v_mul_f32_e32 v28, v1, v1
	v_pk_add_f32 v[86:87], v[28:29], v[86:87] op_sel_hi:[0,1]
	v_mov_b32_e32 v9, v86
	s_nop 1
	v_permlane32_swap_b32_e32 v86, v9
	v_add_f32_e32 v9, v86, v9
	v_fmamk_f32 v9, v9, 0x3c000000, v197
	v_mul_f32_e32 v28, 0x4b800000, v9
	v_cmp_gt_f32_e32 vcc, s78, v9
	s_mov_b32 s78, s65
	s_nop 0
	v_cndmask_b32_e32 v9, v9, v28, vcc
	v_rsq_f32_e32 v9, v9
	s_nop 0
	v_mul_f32_e32 v28, 0x45800000, v9
	v_cndmask_b32_e32 v9, v9, v28, vcc
	v_mul_f32_e32 v28, 0x3e0293ee, v9
	v_pk_mul_f32 v[60:61], v[28:29], v[60:61] op_sel_hi:[0,1]
	s_waitcnt vmcnt(18)
; __device__ __forceinline__ void attn_dense_body(const bf16* Qb, const bf16* __restrict__ Kh, const bf16* __restrict__ Vh,
;                                                 bf16* Ob, int seq, char* lds, const float* __restrict__ qg, const float* __restrict__ rope, int s0) {
;     ...
;     for (int d0 = 0; d0 < 8; ++d0) {
;       const float4 g0 = *reinterpret_cast<const float4*>(gp + d0 * 16), g1 = *reinterpret_cast<const float4*>(gp + d0 * 16 + 4);
;       const float4 c0 = *reinterpret_cast<const float4*>(rp + d0 * 16), c1 = *reinterpret_cast<const float4*>(rp + d0 * 16 + 4);
;       const float gg[8] = {g0.x, g0.y, g0.z, g0.w, g1.x, g1.y, g1.z, g1.w};
;       const float cs[8] = {c0.x, c0.y, c0.z, c0.w, c1.x, c1.y, c1.z, c1.w};
;       unsigned w[4];
; #pragma unroll
;       for (int p = 0; p < 4; ++p) {
;         const float y0 = __uint_as_float((unsigned)(unsigned short)qr[d0][2 * p] << 16) * rstd * gg[2 * p], y1 = __uint_as_float((unsigned)(unsigned short)qr[d0][2 * p + 1] << 16) * rstd * gg[2 * p + 1];
;         w[p] = cvtpk(y0 * cs[2 * p] - y1 * cs[2 * p + 1], y0 * cs[2 * p + 1] + y1 * cs[2 * p]);
;       }
;       u32x4 ww = {w[0], w[1], w[2], w[3]}; qr[d0] = *reinterpret_cast<bf16x8*>(&ww);
	v_pk_mul_f32 v[60:61], v[64:65], v[60:61]
	v_pk_mul_f32 v[52:53], v[28:29], v[52:53] op_sel_hi:[0,1]
	s_waitcnt vmcnt(16)
	v_pk_mul_f32 v[64:65], v[72:73], v[60:61]
	v_pk_mul_f32 v[60:61], v[72:73], v[60:61] op_sel:[0,1] op_sel_hi:[1,0]
	v_sub_f32_e32 v9, v64, v65
	v_add_f32_e32 v60, v60, v61
	v_cvt_pk_bf16_f32 v146, v9, v60
	v_pk_mul_f32 v[60:61], v[28:29], v[84:85] op_sel_hi:[0,1]
	v_pk_mul_f32 v[60:61], v[66:67], v[60:61]
	v_pk_mul_f32 v[50:51], v[28:29], v[50:51] op_sel_hi:[0,1]
	v_pk_mul_f32 v[64:65], v[74:75], v[60:61]
	v_pk_mul_f32 v[60:61], v[74:75], v[60:61] op_sel:[0,1] op_sel_hi:[1,0]
	v_sub_f32_e32 v9, v64, v65
	v_add_f32_e32 v60, v60, v61
	v_cvt_pk_bf16_f32 v147, v9, v60
	v_pk_mul_f32 v[60:61], v[28:29], v[62:63] op_sel_hi:[0,1]
	v_pk_mul_f32 v[54:55], v[54:55], v[60:61]
	v_pk_mul_f32 v[48:49], v[28:29], v[48:49] op_sel_hi:[0,1]
	v_pk_mul_f32 v[60:61], v[54:55], v[68:69]
	v_pk_mul_f32 v[54:55], v[54:55], v[68:69] op_sel:[1,0] op_sel_hi:[0,1]
	v_add_f32_e32 v54, v54, v55
	v_sub_f32_e32 v9, v60, v61
	v_cvt_pk_bf16_f32 v148, v9, v54
	v_pk_mul_f32 v[54:55], v[28:29], v[58:59] op_sel_hi:[0,1]
	v_pk_mul_f32 v[54:55], v[56:57], v[54:55]
	v_pk_mul_f32 v[46:47], v[28:29], v[46:47] op_sel_hi:[0,1]
	v_pk_mul_f32 v[56:57], v[54:55], v[70:71]
	v_pk_mul_f32 v[54:55], v[54:55], v[70:71] op_sel:[1,0] op_sel_hi:[0,1]
	v_add_f32_e32 v54, v54, v55
	v_sub_f32_e32 v9, v56, v57
	v_cvt_pk_bf16_f32 v149, v9, v54
	v_pk_mul_f32 v[70:71], v[28:29], v[82:83] op_sel_hi:[0,1]
	v_pk_mul_f32 v[44:45], v[28:29], v[44:45] op_sel_hi:[0,1]
	v_pk_mul_f32 v[42:43], v[28:29], v[42:43] op_sel_hi:[0,1]
	v_pk_mul_f32 v[40:41], v[28:29], v[40:41] op_sel_hi:[0,1]
	v_pk_mul_f32 v[38:39], v[28:29], v[38:39] op_sel_hi:[0,1]
	v_pk_mul_f32 v[36:37], v[28:29], v[36:37] op_sel_hi:[0,1]
	v_pk_mul_f32 v[34:35], v[28:29], v[34:35] op_sel_hi:[0,1]
	v_pk_mul_f32 v[32:33], v[28:29], v[32:33] op_sel_hi:[0,1]
	v_pk_mul_f32 v[30:31], v[28:29], v[30:31] op_sel_hi:[0,1]
	v_pk_mul_f32 v[26:27], v[28:29], v[26:27] op_sel_hi:[0,1]
	v_pk_mul_f32 v[24:25], v[28:29], v[24:25] op_sel_hi:[0,1]
	v_pk_mul_f32 v[22:23], v[28:29], v[22:23] op_sel_hi:[0,1]
	v_pk_mul_f32 v[20:21], v[28:29], v[20:21] op_sel_hi:[0,1]
	v_pk_mul_f32 v[18:19], v[28:29], v[18:19] op_sel_hi:[0,1]
	v_pk_mul_f32 v[16:17], v[28:29], v[16:17] op_sel_hi:[0,1]
	v_pk_mul_f32 v[14:15], v[28:29], v[14:15] op_sel_hi:[0,1]
	v_pk_mul_f32 v[12:13], v[28:29], v[12:13] op_sel_hi:[0,1]
	v_pk_mul_f32 v[6:7], v[28:29], v[6:7] op_sel_hi:[0,1]
	v_pk_mul_f32 v[4:5], v[28:29], v[4:5] op_sel_hi:[0,1]
	v_pk_mul_f32 v[2:3], v[28:29], v[2:3] op_sel_hi:[0,1]
	v_pk_mul_f32 v[0:1], v[28:29], v[0:1] op_sel_hi:[0,1]
	s_waitcnt vmcnt(15)
	v_pk_mul_f32 v[54:55], v[70:71], v[96:97]
	s_waitcnt vmcnt(14)
	v_pk_mul_f32 v[70:71], v[54:55], v[100:101]
	v_pk_mul_f32 v[54:55], v[54:55], v[100:101] op_sel:[1,0] op_sel_hi:[0,1]
	v_add_f32_e32 v54, v54, v55
	v_sub_f32_e32 v9, v70, v71
	v_cvt_pk_bf16_f32 v150, v9, v54
	v_pk_mul_f32 v[54:55], v[28:29], v[80:81] op_sel_hi:[0,1]
	v_pk_mul_f32 v[54:55], v[54:55], v[98:99]
	s_nop 0
	v_pk_mul_f32 v[56:57], v[54:55], v[102:103]
	v_pk_mul_f32 v[54:55], v[54:55], v[102:103] op_sel:[1,0] op_sel_hi:[0,1]
	v_add_f32_e32 v54, v54, v55
	v_sub_f32_e32 v9, v56, v57
	v_cvt_pk_bf16_f32 v151, v9, v54
	v_pk_mul_f32 v[54:55], v[28:29], v[78:79] op_sel_hi:[0,1]
	s_waitcnt vmcnt(13)
	v_pk_mul_f32 v[54:55], v[54:55], v[104:105]
	s_waitcnt vmcnt(12)
	v_pk_mul_f32 v[56:57], v[54:55], v[108:109]
	v_pk_mul_f32 v[54:55], v[54:55], v[108:109] op_sel:[1,0] op_sel_hi:[0,1]
	v_add_f32_e32 v54, v54, v55
	v_sub_f32_e32 v9, v56, v57
	v_cvt_pk_bf16_f32 v152, v9, v54
	v_pk_mul_f32 v[54:55], v[28:29], v[76:77] op_sel_hi:[0,1]
	v_pk_mul_f32 v[54:55], v[54:55], v[106:107]
	s_nop 0
	v_pk_mul_f32 v[56:57], v[54:55], v[110:111]
	v_pk_mul_f32 v[54:55], v[54:55], v[110:111] op_sel:[1,0] op_sel_hi:[0,1]
	v_add_f32_e32 v54, v54, v55
	v_sub_f32_e32 v9, v56, v57
	v_cvt_pk_bf16_f32 v153, v9, v54
	global_load_dwordx4 v[96:99], v8, s[16:17] offset:320
	global_load_dwordx4 v[100:103], v8, s[16:17] offset:336
	global_load_dwordx4 v[104:107], v[10:11], off offset:320
	global_load_dwordx4 v[108:111], v[10:11], off offset:336
	s_waitcnt vmcnt(15)
	v_pk_mul_f32 v[52:53], v[52:53], v[124:125]
	v_pk_mul_f32 v[50:51], v[50:51], v[126:127]
	s_waitcnt vmcnt(14)
	v_pk_mul_f32 v[48:49], v[48:49], v[128:129]
	v_pk_mul_f32 v[46:47], v[46:47], v[130:131]
	s_waitcnt vmcnt(13)
	v_pk_mul_f32 v[54:55], v[52:53], v[132:133]
	v_pk_mul_f32 v[52:53], v[52:53], v[132:133] op_sel:[1,0] op_sel_hi:[0,1]
	v_pk_mul_f32 v[56:57], v[50:51], v[134:135]
	v_pk_mul_f32 v[50:51], v[50:51], v[134:135] op_sel:[1,0] op_sel_hi:[0,1]
	s_waitcnt vmcnt(12)
	v_pk_mul_f32 v[58:59], v[48:49], v[136:137]
	v_pk_mul_f32 v[48:49], v[48:49], v[136:137] op_sel:[1,0] op_sel_hi:[0,1]
	v_pk_mul_f32 v[60:61], v[46:47], v[138:139]
	v_pk_mul_f32 v[46:47], v[46:47], v[138:139] op_sel:[1,0] op_sel_hi:[0,1]
	v_add_f32_e32 v52, v52, v53
	v_sub_f32_e32 v53, v56, v57
	v_add_f32_e32 v50, v50, v51
	v_sub_f32_e32 v51, v58, v59
	v_add_f32_e32 v48, v48, v49
	v_sub_f32_e32 v49, v60, v61
	v_add_f32_e32 v46, v46, v47
	v_sub_f32_e32 v9, v54, v55
	v_cvt_pk_bf16_f32 v154, v9, v52
	v_cvt_pk_bf16_f32 v155, v53, v50
	v_cvt_pk_bf16_f32 v156, v51, v48
	v_cvt_pk_bf16_f32 v157, v49, v46
	global_load_dwordx4 v[124:127], v8, s[16:17] offset:384
	global_load_dwordx4 v[128:131], v8, s[16:17] offset:400
	global_load_dwordx4 v[132:135], v[10:11], off offset:384
	global_load_dwordx4 v[136:139], v[10:11], off offset:400
	s_waitcnt vmcnt(15)
	v_pk_mul_f32 v[44:45], v[44:45], v[88:89]
	v_pk_mul_f32 v[42:43], v[42:43], v[90:91]
	s_waitcnt vmcnt(14)
; __device__ __forceinline__ void attn_dense_body(const bf16* Qb, const bf16* __restrict__ Kh, const bf16* __restrict__ Vh,
;                                                 bf16* Ob, int seq, char* lds, const float* __restrict__ qg, const float* __restrict__ rope, int s0) {
;     ...
;     for (int d0 = 0; d0 < 8; ++d0) {
;       const float4 g0 = *reinterpret_cast<const float4*>(gp + d0 * 16), g1 = *reinterpret_cast<const float4*>(gp + d0 * 16 + 4);
;       const float4 c0 = *reinterpret_cast<const float4*>(rp + d0 * 16), c1 = *reinterpret_cast<const float4*>(rp + d0 * 16 + 4);
;       const float gg[8] = {g0.x, g0.y, g0.z, g0.w, g1.x, g1.y, g1.z, g1.w};
;       const float cs[8] = {c0.x, c0.y, c0.z, c0.w, c1.x, c1.y, c1.z, c1.w};
;       unsigned w[4];
; #pragma unroll
;       for (int p = 0; p < 4; ++p) {
;         const float y0 = __uint_as_float((unsigned)(unsigned short)qr[d0][2 * p] << 16) * rstd * gg[2 * p], y1 = __uint_as_float((unsigned)(unsigned short)qr[d0][2 * p + 1] << 16) * rstd * gg[2 * p + 1];
;         w[p] = cvtpk(y0 * cs[2 * p] - y1 * cs[2 * p + 1], y0 * cs[2 * p + 1] + y1 * cs[2 * p]);
;       }
;       u32x4 ww = {w[0], w[1], w[2], w[3]}; qr[d0] = *reinterpret_cast<bf16x8*>(&ww);
	v_pk_mul_f32 v[40:41], v[40:41], v[92:93]
	v_pk_mul_f32 v[38:39], v[38:39], v[94:95]
	s_waitcnt vmcnt(13)
	v_pk_mul_f32 v[46:47], v[44:45], v[112:113]
	v_pk_mul_f32 v[44:45], v[44:45], v[112:113] op_sel:[1,0] op_sel_hi:[0,1]
	v_pk_mul_f32 v[48:49], v[42:43], v[114:115]
	v_pk_mul_f32 v[42:43], v[42:43], v[114:115] op_sel:[1,0] op_sel_hi:[0,1]
	s_waitcnt vmcnt(12)
	v_pk_mul_f32 v[50:51], v[40:41], v[140:141]
	v_pk_mul_f32 v[40:41], v[40:41], v[140:141] op_sel:[1,0] op_sel_hi:[0,1]
	v_pk_mul_f32 v[52:53], v[38:39], v[142:143]
	v_pk_mul_f32 v[38:39], v[38:39], v[142:143] op_sel:[1,0] op_sel_hi:[0,1]
	v_add_f32_e32 v44, v44, v45
	v_sub_f32_e32 v45, v48, v49
	v_add_f32_e32 v42, v42, v43
	v_sub_f32_e32 v43, v50, v51
	v_add_f32_e32 v40, v40, v41
	v_sub_f32_e32 v41, v52, v53
	v_add_f32_e32 v38, v38, v39
	v_sub_f32_e32 v9, v46, v47
	v_cvt_pk_bf16_f32 v158, v9, v44
	v_cvt_pk_bf16_f32 v159, v45, v42
	v_cvt_pk_bf16_f32 v160, v43, v40
	v_cvt_pk_bf16_f32 v161, v41, v38
	global_load_dwordx4 v[88:91], v8, s[16:17] offset:448
	global_load_dwordx4 v[92:95], v8, s[16:17] offset:464
	global_load_dwordx4 v[112:115], v[10:11], off offset:448
	global_load_dwordx4 v[140:143], v[10:11], off offset:464
	s_waitcnt vmcnt(15)
	v_pk_mul_f32 v[36:37], v[36:37], v[178:179]
	v_pk_mul_f32 v[34:35], v[34:35], v[180:181]
	s_waitcnt vmcnt(14)
	v_pk_mul_f32 v[32:33], v[32:33], v[182:183]
	v_pk_mul_f32 v[30:31], v[30:31], v[184:185]
	s_waitcnt vmcnt(13)
	v_pk_mul_f32 v[38:39], v[36:37], v[186:187]
	v_pk_mul_f32 v[36:37], v[36:37], v[186:187] op_sel:[1,0] op_sel_hi:[0,1]
	v_pk_mul_f32 v[40:41], v[34:35], v[188:189]
	v_pk_mul_f32 v[34:35], v[34:35], v[188:189] op_sel:[1,0] op_sel_hi:[0,1]
	s_waitcnt vmcnt(12)
	v_pk_mul_f32 v[42:43], v[32:33], v[242:243]
	v_pk_mul_f32 v[32:33], v[32:33], v[242:243] op_sel:[1,0] op_sel_hi:[0,1]
	v_pk_mul_f32 v[44:45], v[30:31], v[244:245]
	v_pk_mul_f32 v[30:31], v[30:31], v[244:245] op_sel:[1,0] op_sel_hi:[0,1]
	v_add_f32_e32 v36, v36, v37
	v_sub_f32_e32 v37, v40, v41
	v_add_f32_e32 v34, v34, v35
	v_sub_f32_e32 v35, v42, v43
	v_add_f32_e32 v32, v32, v33
	v_sub_f32_e32 v33, v44, v45
	v_add_f32_e32 v30, v30, v31
	v_sub_f32_e32 v9, v38, v39
	v_cvt_pk_bf16_f32 v162, v9, v36
	v_cvt_pk_bf16_f32 v163, v37, v34
	v_cvt_pk_bf16_f32 v164, v35, v32
	v_cvt_pk_bf16_f32 v165, v33, v30
	s_waitcnt vmcnt(11)
	v_pk_mul_f32 v[26:27], v[26:27], v[96:97]
	v_pk_mul_f32 v[24:25], v[24:25], v[98:99]
	s_waitcnt vmcnt(10)
	v_pk_mul_f32 v[22:23], v[22:23], v[100:101]
	v_pk_mul_f32 v[20:21], v[20:21], v[102:103]
	s_waitcnt vmcnt(9)
	v_pk_mul_f32 v[30:31], v[26:27], v[104:105]
	v_pk_mul_f32 v[26:27], v[26:27], v[104:105] op_sel:[1,0] op_sel_hi:[0,1]
	v_pk_mul_f32 v[32:33], v[24:25], v[106:107]
	v_pk_mul_f32 v[24:25], v[24:25], v[106:107] op_sel:[1,0] op_sel_hi:[0,1]
	s_waitcnt vmcnt(8)
	v_pk_mul_f32 v[34:35], v[22:23], v[108:109]
	v_pk_mul_f32 v[22:23], v[22:23], v[108:109] op_sel:[1,0] op_sel_hi:[0,1]
	v_pk_mul_f32 v[36:37], v[20:21], v[110:111]
	v_pk_mul_f32 v[20:21], v[20:21], v[110:111] op_sel:[1,0] op_sel_hi:[0,1]
	v_add_f32_e32 v26, v26, v27
	v_sub_f32_e32 v27, v32, v33
	v_add_f32_e32 v24, v24, v25
	v_sub_f32_e32 v25, v34, v35
	v_add_f32_e32 v22, v22, v23
	v_sub_f32_e32 v23, v36, v37
	v_add_f32_e32 v20, v20, v21
	v_sub_f32_e32 v9, v30, v31
	v_cvt_pk_bf16_f32 v166, v9, v26
	v_cvt_pk_bf16_f32 v167, v27, v24
	v_cvt_pk_bf16_f32 v168, v25, v22
	v_cvt_pk_bf16_f32 v169, v23, v20
	s_waitcnt vmcnt(7)
	v_pk_mul_f32 v[18:19], v[18:19], v[124:125]
	v_pk_mul_f32 v[16:17], v[16:17], v[126:127]
	s_waitcnt vmcnt(6)
	v_pk_mul_f32 v[14:15], v[14:15], v[128:129]
	v_pk_mul_f32 v[12:13], v[12:13], v[130:131]
	s_waitcnt vmcnt(5)
	v_pk_mul_f32 v[20:21], v[18:19], v[132:133]
	v_pk_mul_f32 v[18:19], v[18:19], v[132:133] op_sel:[1,0] op_sel_hi:[0,1]
	v_pk_mul_f32 v[22:23], v[16:17], v[134:135]
	v_pk_mul_f32 v[16:17], v[16:17], v[134:135] op_sel:[1,0] op_sel_hi:[0,1]
	s_waitcnt vmcnt(4)
	v_pk_mul_f32 v[24:25], v[14:15], v[136:137]
	v_pk_mul_f32 v[14:15], v[14:15], v[136:137] op_sel:[1,0] op_sel_hi:[0,1]
	v_pk_mul_f32 v[26:27], v[12:13], v[138:139]
	v_pk_mul_f32 v[12:13], v[12:13], v[138:139] op_sel:[1,0] op_sel_hi:[0,1]
	v_sub_f32_e32 v9, v20, v21
	v_add_f32_e32 v18, v18, v19
	v_sub_f32_e32 v19, v22, v23
	v_add_f32_e32 v16, v16, v17
	v_sub_f32_e32 v17, v24, v25
	v_add_f32_e32 v14, v14, v15
	v_sub_f32_e32 v15, v26, v27
	v_add_f32_e32 v12, v12, v13
	v_cvt_pk_bf16_f32 v170, v9, v18
	v_cvt_pk_bf16_f32 v171, v19, v16
	v_cvt_pk_bf16_f32 v172, v17, v14
	v_cvt_pk_bf16_f32 v173, v15, v12
	s_nop 0
	v_ashrrev_i32_e32 v24, 4, v29
	v_lshlrev_b32_e32 v25, 3, v29
	v_and_b32_e32 v26, 0x78, v25
	v_lshlrev_b32_e32 v27, 8, v24
	v_or_b32_e32 v30, v27, v26
	v_lshlrev_b32_e32 v214, 1, v30
	v_add_u32_e32 v215, 0x4000, v214
	s_waitcnt vmcnt(3)
	v_pk_mul_f32 v[6:7], v[6:7], v[88:89]
	v_pk_mul_f32 v[4:5], v[4:5], v[90:91]
	s_waitcnt vmcnt(2)
	v_pk_mul_f32 v[2:3], v[2:3], v[92:93]
	v_pk_mul_f32 v[0:1], v[0:1], v[94:95]
	s_waitcnt vmcnt(1)
	v_pk_mul_f32 v[12:13], v[6:7], v[112:113]
	v_pk_mul_f32 v[6:7], v[6:7], v[112:113] op_sel:[1,0] op_sel_hi:[0,1]
	v_pk_mul_f32 v[14:15], v[4:5], v[114:115]
	v_pk_mul_f32 v[4:5], v[4:5], v[114:115] op_sel:[1,0] op_sel_hi:[0,1]
	s_waitcnt vmcnt(0)
; __device__ __forceinline__ int v_st(int k, int c) { const int kk = (k & ~0xC) | ((k & 4) << 1) | ((k & 8) >> 1); return ((kk >> 3) * 4 + (c >> 5)) * 512 + ((kk & 7) * 32 + (c & 31)) * 2; }
; __device__ __forceinline__ int v_rd_base(int lane) { return ((lane & 3) << 3) | (((lane >> 2) & 3) << 6) | (((lane >> 4) & 1) << 5) | (((lane >> 5) & 1) << 8); }
; __device__ __forceinline__ void qkt(f32x16& p0, f32x16& p1, const bf16* Ks, const bf16x8* qr, const f32x16& negm, int r32, int hi) {
; #pragma unroll
;   for (int d0 = 0; d0 < 8; ++d0) { int cb = (d0 * 16 + hi * 8) * 2;
;     bf16x8 b0 = *reinterpret_cast<const bf16x8*>((const char*)Ks + KSWZ(r32, cb));
;     bf16x8 b1 = *reinterpret_cast<const bf16x8*>((const char*)Ks + KSWZ(32 + r32, cb));
;     if (d0 == 0) { p0 = __builtin_amdgcn_mfma_f32_32x32x16_bf16(b0, qr[0], negm, 0, 0, 0); p1 = __builtin_amdgcn_mfma_f32_32x32x16_bf16(b1, qr[0], negm, 0, 0, 0); }
;     else { p0 = __builtin_amdgcn_mfma_f32_32x32x16_bf16(b0, qr[d0], p0, 0, 0, 0); p1 = __builtin_amdgcn_mfma_f32_32x32x16_bf16(b1, qr[d0], p1, 0, 0, 0); } }
; }
; __device__ __forceinline__ void attn_dense_body(const bf16* Qb, const bf16* __restrict__ Kh, const bf16* __restrict__ Vh,
;                                                 bf16* Ob, int seq, char* lds, const float* __restrict__ qg, const float* __restrict__ rope, int s0) {
;     ...
;   const int sr = tid >> 4, sc = (tid & 15) * 8, vst0 = v_st(sr, sc), vst1 = v_st(32 + sr, sc);
;   const int vb0 = (int)(uintptr_t)V_lds + v_rd_base(lane);
;   struct { bf16x8 vs0, vs1, ks0, ks1; } sr_[1];
;   const __amdgpu_buffer_rsrc_t srK = __builtin_amdgcn_make_buffer_rsrc((void*)Kh, (short)0, seq * LDK * 2, 0x00020000);
;   const __amdgpu_buffer_rsrc_t srV = __builtin_amdgcn_make_buffer_rsrc((void*)Vh, (short)0, seq * LDK * 2, 0x00020000);
;   const unsigned kvoff = (unsigned)(sr * LDK + sc) * 2u;
;     ...
;   f32x16 pA0, pA1, pB0, pB1; float alA, alB; bf16x8 pa0, pa1, pa2, pa3; const int NT = seq / KVBLK;
;   constexpr int SE = 0, SO = 0;
;   SLOAD(SE, 0); asm volatile("s_waitcnt vmcnt(0)" ::: "memory"); SWRITE(0, SE); __syncthreads();
;   qkt(pA0, pA1, K_lds, qr, negm, r32, hi); partialSM<true>(pA0, pA1, m_reg, negm, alA);
;   SLOAD(SO, KVBLK);
	v_pk_mul_f32 v[16:17], v[2:3], v[140:141]
	v_pk_mul_f32 v[2:3], v[2:3], v[140:141] op_sel:[1,0] op_sel_hi:[0,1]
	v_pk_mul_f32 v[8:9], v[0:1], v[142:143]
	v_pk_mul_f32 v[0:1], v[0:1], v[142:143] op_sel:[1,0] op_sel_hi:[0,1]
	v_sub_f32_e32 v10, v12, v13
	v_add_f32_e32 v6, v6, v7
	v_sub_f32_e32 v7, v14, v15
	v_add_f32_e32 v4, v4, v5
	v_sub_f32_e32 v5, v16, v17
	v_add_f32_e32 v2, v2, v3
	v_sub_f32_e32 v3, v8, v9
	v_add_f32_e32 v0, v0, v1
	v_cvt_pk_bf16_f32 v174, v10, v6
	v_cvt_pk_bf16_f32 v175, v7, v4
	v_cvt_pk_bf16_f32 v176, v5, v2
	v_cvt_pk_bf16_f32 v177, v3, v0
	buffer_load_dwordx4 v[0:3], v214, s[92:95], 0 offen
	buffer_load_dwordx4 v[4:7], v215, s[92:95], 0 offen
	buffer_load_dwordx4 v[8:11], v214, s[56:59], 0 offen
	buffer_load_dwordx4 v[12:15], v215, s[56:59], 0 offen
	v_and_b32_e32 v17, 0xfffff0, v24
	v_lshlrev_b32_e32 v18, 1, v24
	v_lshrrev_b32_e32 v19, 1, v24
	v_and_b32_e32 v21, 3, v24
	v_add_u32_e32 v22, 32, v24
	v_and_or_b32 v17, v18, 8, v17
	v_and_or_b32 v18, v19, 4, v21
	v_and_b32_e32 v21, 0xfffff0, v22
	v_lshlrev_b32_e32 v23, 1, v22
	v_and_b32_e32 v16, 0x70, v29
	v_bfe_u32 v20, v25, 5, 2
	v_lshlrev_b32_e32 v19, 1, v26
	v_lshlrev_b32_e32 v22, 8, v22
	v_lshrrev_b32_e32 v17, 1, v17
	v_and_or_b32 v21, v23, 8, v21
	v_and_b32_e32 v25, 48, v19
	v_bitop3_b32 v23, v19, v27, v16 bitop3:0xde
	v_bitop3_b32 v16, v19, v22, v16 bitop3:0xde
	v_or_b32_e32 v17, v17, v20
	v_lshrrev_b32_e32 v19, 1, v21
	v_lshlrev_b32_e32 v18, 6, v18
	v_add_u32_e32 v218, 0, v16
	v_lshlrev_b32_e32 v16, 9, v17
	v_or_b32_e32 v17, v19, v20
	v_bitop3_b32 v24, v194, v116, v117 bitop3:0xde
	v_or3_b32 v16, v16, v18, v25
	v_lshlrev_b32_e32 v17, 9, v17
	v_add_u32_e32 v216, 0, v24
	v_or3_b32 v17, v17, v18, v25
	v_add_u32_e32 v219, 0, v16
	v_add_u32_e32 v217, 0, v23
	v_add_u32_e32 v220, 0, v17
	s_waitcnt vmcnt(0)
	s_waitcnt vmcnt(3)
	ds_write_b128 v219, v[0:3]
	s_waitcnt vmcnt(2)
	ds_write_b128 v220, v[4:7]
	s_waitcnt vmcnt(1)
	ds_write_b128 v217, v[8:11] offset:32768
	s_waitcnt vmcnt(0)
	ds_write_b128 v218, v[12:15] offset:32768
	s_waitcnt lgkmcnt(0)
	s_barrier
	ds_read_b128 v[0:3], v216 offset:32768
	ds_read_b128 v[4:7], v216 offset:40960
	s_waitcnt lgkmcnt(1)
	v_mfma_f32_32x32x16_bf16 v[80:95], v[0:3], v[146:149], 0
	v_or_b32_e32 v0, 32, v194
	v_bitop3_b32 v0, v0, v116, v117 bitop3:0xde
	v_add_u32_e32 v224, 0, v0
	s_waitcnt lgkmcnt(0)
	v_mfma_f32_32x32x16_bf16 v[64:79], v[4:7], v[146:149], 0
	ds_read_b128 v[0:3], v224 offset:32768
	ds_read_b128 v[4:7], v224 offset:40960
	s_waitcnt lgkmcnt(1)
	v_mfma_f32_32x32x16_bf16 v[80:95], v[0:3], v[150:153], v[80:95]
	v_or_b32_e32 v0, 64, v194
	v_bitop3_b32 v0, v0, v116, v117 bitop3:0xde
	v_add_u32_e32 v223, 0, v0
	s_waitcnt lgkmcnt(0)
	v_mfma_f32_32x32x16_bf16 v[64:79], v[4:7], v[150:153], v[64:79]
	ds_read_b128 v[0:3], v223 offset:32768
	ds_read_b128 v[4:7], v223 offset:40960
	s_waitcnt lgkmcnt(1)
	v_mfma_f32_32x32x16_bf16 v[80:95], v[0:3], v[154:157], v[80:95]
	v_or_b32_e32 v0, 0x60, v194
	v_bitop3_b32 v0, v0, v116, v117 bitop3:0xde
	v_add_u32_e32 v221, 0, v0
	s_waitcnt lgkmcnt(0)
	v_mfma_f32_32x32x16_bf16 v[64:79], v[4:7], v[154:157], v[64:79]
	ds_read_b128 v[0:3], v221 offset:32768
	ds_read_b128 v[4:7], v221 offset:40960
	buffer_load_dwordx4 v[96:99], v214, s[92:95], s64 offen
	buffer_load_dwordx4 v[100:103], v215, s[92:95], s64 offen
	buffer_load_dwordx4 v[104:107], v214, s[56:59], s64 offen
	buffer_load_dwordx4 v[108:111], v215, s[56:59], s64 offen
	s_mov_b32 s64, s65
	s_waitcnt lgkmcnt(1)
	v_mfma_f32_32x32x16_bf16 v[80:95], v[0:3], v[158:161], v[80:95]
	v_or_b32_e32 v0, 0x80, v194
	v_bitop3_b32 v0, v0, v116, v117 bitop3:0xde
	v_add_u32_e32 v222, 0, v0
	ds_read_b128 v[0:3], v222 offset:32768
	s_waitcnt lgkmcnt(1)
	v_mfma_f32_32x32x16_bf16 v[64:79], v[4:7], v[158:161], v[64:79]
	ds_read_b128 v[4:7], v222 offset:40960
	s_waitcnt lgkmcnt(1)
	v_mfma_f32_32x32x16_bf16 v[80:95], v[0:3], v[162:165], v[80:95]
	v_or_b32_e32 v0, 0xa0, v194
	v_bitop3_b32 v0, v0, v116, v117 bitop3:0xde
	v_add_u32_e32 v225, 0, v0
	ds_read_b128 v[0:3], v225 offset:32768
	s_waitcnt lgkmcnt(1)
	v_mfma_f32_32x32x16_bf16 v[64:79], v[4:7], v[162:165], v[64:79]
	ds_read_b128 v[4:7], v225 offset:40960
	s_waitcnt lgkmcnt(1)
	v_mfma_f32_32x32x16_bf16 v[80:95], v[0:3], v[166:169], v[80:95]
	v_or_b32_e32 v0, 0xc0, v194
	v_bitop3_b32 v0, v0, v116, v117 bitop3:0xde
	v_add_u32_e32 v226, 0, v0
	ds_read_b128 v[16:19], v226 offset:32768
	ds_read_b128 v[112:115], v226 offset:40960
	v_bitop3_b32 v116, v118, v116, v117 bitop3:0xde
	v_add_u32_e32 v227, 0, v116
	s_waitcnt lgkmcnt(2)
	v_mfma_f32_32x32x16_bf16 v[64:79], v[4:7], v[166:169], v[64:79]
	ds_read_b128 v[116:119], v227 offset:32768
	v_mov_b64_e32 v[0:1], s[64:65]
	v_mov_b64_e32 v[14:15], s[78:79]
	v_mov_b64_e32 v[2:3], s[66:67]
	v_mov_b64_e32 v[4:5], s[68:69]
	v_mov_b64_e32 v[6:7], s[70:71]
	v_mov_b64_e32 v[8:9], s[72:73]
	s_waitcnt lgkmcnt(2)
	v_mfma_f32_32x32x16_bf16 v[80:95], v[16:19], v[170:173], v[80:95]
	v_mov_b64_e32 v[10:11], s[74:75]
	v_mov_b64_e32 v[12:13], s[76:77]
	v_mov_b64_e32 v[46:47], v[14:15]
	v_mov_b64_e32 v[30:31], v[14:15]
	v_mov_b64_e32 v[62:63], v[14:15]
	s_mov_b32 s78, 0x800000
	s_mov_b32 s64, 0x8000
	s_waitcnt lgkmcnt(1)
	v_mfma_f32_32x32x16_bf16 v[64:79], v[112:115], v[170:173], v[64:79]
	v_lshlrev_b32_e32 v112, 3, v121
	v_and_b32_e32 v113, 0xc0, v120
	v_and_b32_e32 v120, 32, v123
	v_and_or_b32 v121, v112, 24, v113
	v_and_b32_e32 v123, 0x100, v112
	ds_read_b128 v[112:115], v227 offset:40960
	s_waitcnt vmcnt(0)
	s_waitcnt lgkmcnt(1)
	v_mfma_f32_32x32x16_bf16 v[80:95], v[116:119], v[174:177], v[80:95]
	s_waitcnt vmcnt(3)
	ds_write_b128 v219, v[96:99] offset:16384
	s_waitcnt vmcnt(2)
; #define SLOAD(i, k0) do { const unsigned so_ = (unsigned)(k0) * (LDK * 2); \
;     sr_[i].vs0 = BLD8(srV, kvoff, so_); sr_[i].vs1 = BLD8(srV, kvoff + 32u * LDK * 2u, so_); \
;     sr_[i].ks0 = BLD8(srK, kvoff, so_); sr_[i].ks1 = BLD8(srK, kvoff + 32u * LDK * 2u, so_); } while (0)
; #define SWRITE(b, i) do { *(bf16x8*)((char*)V_lds + (b) * SHM_V + vst0) = sr_[i].vs0;          \
;     *(bf16x8*)((char*)V_lds + (b) * SHM_V + vst1) = sr_[i].vs1; int kc = sc * 2;               \
;     *(bf16x8*)((char*)K_lds + (b) * SHM_K + KSWZ(sr, kc)) = sr_[i].ks0;                       \
;     *(bf16x8*)((char*)K_lds + (b) * SHM_K + KSWZ(32 + sr, kc)) = sr_[i].ks1; } while (0)
; #define SWAIT() asm volatile("s_waitcnt vmcnt(0)" ::: "memory")
; template <bool FIRST>
; __device__ __forceinline__ void partialSM(f32x16& p0, f32x16& p1, float& m_reg, f32x16& negm, float& alpha) {
;   float pmax = p0[0]; for (int r = 1; r < 16; ++r) pmax = fmaxf(pmax, p0[r]); for (int r = 0; r < 16; ++r) pmax = fmaxf(pmax, p1[r]);
;   { auto rr = __builtin_amdgcn_permlane32_swap(__float_as_uint(pmax), __float_as_uint(pmax), false, false);
;     pmax = fmaxf(__uint_as_float(rr[0]), __uint_as_float(rr[1])); }
;   if (!FIRST && __builtin_expect(__all(pmax <= THRL), 1)) { alpha = 1.f; }
;   else {
;     const float d = FIRST ? pmax : fmaxf(pmax, 0.f);
;     alpha = FIRST ? 1.f : __builtin_amdgcn_exp2f(-d);
;     m_reg += d;
;     for (int r = 0; r < 16; ++r) p0[r] -= d; for (int r = 0; r < 16; ++r) p1[r] -= d;
;     const float nm = -m_reg; for (int r = 0; r < 16; ++r) negm[r] = nm;
;   }
;   for (int r = 0; r < 16; ++r) p0[r] = __builtin_amdgcn_exp2f(p0[r]);
; }
; __device__ __forceinline__ void attn_dense_body(const bf16* Qb, const bf16* __restrict__ Kh, const bf16* __restrict__ Vh,
;                                                 bf16* Ob, int seq, char* lds, const float* __restrict__ qg, const float* __restrict__ rope, int s0) {
;     ...
;   SLOAD(SE, 0); asm volatile("s_waitcnt vmcnt(0)" ::: "memory"); SWRITE(0, SE); __syncthreads();
;   qkt(pA0, pA1, K_lds, qr, negm, r32, hi); partialSM<true>(pA0, pA1, m_reg, negm, alA);
;   SLOAD(SO, KVBLK);
;   SWAIT(); SWRITE(1, SO); __syncthreads();
	ds_write_b128 v220, v[100:103] offset:16384
	s_waitcnt vmcnt(1)
	ds_write_b128 v217, v[104:107] offset:49152
	s_waitcnt vmcnt(0)
	ds_write_b128 v218, v[108:111] offset:49152
	s_waitcnt lgkmcnt(4)
	v_mfma_f32_32x32x16_bf16 v[64:79], v[112:115], v[174:177], v[64:79]
	s_nop 1
	v_max_f32_e32 v112, v81, v81
	v_max_f32_e32 v113, v80, v80
	v_max_f32_e32 v112, v113, v112
	v_max3_f32 v112, v112, v82, v83
	v_max3_f32 v112, v112, v84, v85
	v_max3_f32 v112, v112, v86, v87
	v_max3_f32 v112, v112, v88, v89
	v_max3_f32 v112, v112, v90, v91
	v_max3_f32 v112, v112, v92, v93
	v_max3_f32 v96, v112, v94, v95
	v_max3_f32 v96, v96, v64, v65
	v_max3_f32 v96, v96, v66, v67
	v_max3_f32 v96, v96, v68, v69
	v_max3_f32 v96, v96, v70, v71
	v_max3_f32 v96, v96, v72, v73
	v_max3_f32 v96, v96, v74, v75
	v_max3_f32 v96, v96, v76, v77
	v_max3_f32 v96, v96, v78, v79
	v_mov_b32_e32 v97, v96
	s_nop 1
	v_permlane32_swap_b32_e32 v96, v97
	v_max_f32_e32 v97, v97, v97
	v_max_f32_e32 v96, v96, v96
	v_max_f32_e32 v96, v96, v97
	v_sub_f32_e32 v112, v80, v96
	v_sub_f32_e32 v81, v81, v96
	v_sub_f32_e32 v82, v82, v96
	v_sub_f32_e32 v83, v83, v96
	v_sub_f32_e32 v84, v84, v96
	v_sub_f32_e32 v85, v85, v96
	v_sub_f32_e32 v86, v86, v96
	v_sub_f32_e32 v87, v87, v96
	v_sub_f32_e32 v88, v88, v96
	v_sub_f32_e32 v89, v89, v96
	v_sub_f32_e32 v90, v90, v96
	v_sub_f32_e32 v91, v91, v96
	v_sub_f32_e32 v92, v92, v96
	v_sub_f32_e32 v93, v93, v96
	v_sub_f32_e32 v94, v94, v96
	v_sub_f32_e32 v95, v95, v96
	v_exp_f32_e32 v245, v112
	v_exp_f32_e32 v247, v81
	v_exp_f32_e32 v179, v82
	v_exp_f32_e32 v246, v83
	v_exp_f32_e32 v180, v84
	v_exp_f32_e32 v244, v85
	v_exp_f32_e32 v181, v86
	v_exp_f32_e32 v243, v87
	v_exp_f32_e32 v240, v88
	v_exp_f32_e32 v242, v89
	v_exp_f32_e32 v239, v90
	v_exp_f32_e32 v241, v91
	v_exp_f32_e32 v236, v92
	v_exp_f32_e32 v238, v93
	v_exp_f32_e32 v235, v94
	v_exp_f32_e32 v237, v95
	v_or3_b32 v116, v121, v120, v123
	v_add_f32_e32 v229, 0, v96
	v_add_u32_e32 v213, s26, v116
	s_addk_i32 s26, 0x4000
	v_xor_b32_e32 v80, 0x80000000, v229
	v_mov_b64_e32 v[44:45], v[12:13]
	v_mov_b64_e32 v[42:43], v[10:11]
	v_mov_b64_e32 v[40:41], v[8:9]
	v_mov_b64_e32 v[38:39], v[6:7]
	v_mov_b64_e32 v[36:37], v[4:5]
	v_mov_b64_e32 v[34:35], v[2:3]
	v_mov_b64_e32 v[32:33], v[0:1]
	v_mov_b64_e32 v[28:29], v[12:13]
	v_mov_b64_e32 v[26:27], v[10:11]
	v_mov_b64_e32 v[24:25], v[8:9]
	v_mov_b64_e32 v[22:23], v[6:7]
	v_mov_b64_e32 v[20:21], v[4:5]
	v_mov_b64_e32 v[18:19], v[2:3]
	v_mov_b64_e32 v[16:17], v[0:1]
	v_mov_b64_e32 v[60:61], v[12:13]
	v_mov_b64_e32 v[58:59], v[10:11]
	v_mov_b64_e32 v[56:57], v[8:9]
	v_mov_b64_e32 v[54:55], v[6:7]
	v_mov_b64_e32 v[52:53], v[4:5]
	v_mov_b64_e32 v[50:51], v[2:3]
	v_mov_b64_e32 v[48:49], v[0:1]
	v_add_u32_e32 v212, s26, v116
	v_sub_f32_e32 v111, v79, v96
	v_sub_f32_e32 v110, v78, v96
	v_sub_f32_e32 v109, v77, v96
	v_sub_f32_e32 v108, v76, v96
	v_sub_f32_e32 v107, v75, v96
	v_sub_f32_e32 v106, v74, v96
	v_sub_f32_e32 v105, v73, v96
	v_sub_f32_e32 v104, v72, v96
	v_sub_f32_e32 v103, v71, v96
	v_sub_f32_e32 v102, v70, v96
	v_sub_f32_e32 v101, v69, v96
	v_sub_f32_e32 v100, v68, v96
	v_sub_f32_e32 v99, v67, v96
	v_sub_f32_e32 v98, v66, v96
	v_sub_f32_e32 v97, v65, v96
	v_sub_f32_e32 v96, v64, v96
	v_mov_b32_e32 v81, v80
	v_mov_b32_e32 v82, v80
	v_mov_b32_e32 v83, v80
	v_mov_b32_e32 v84, v80
	v_mov_b32_e32 v85, v80
	v_mov_b32_e32 v86, v80
	v_mov_b32_e32 v87, v80
	v_mov_b32_e32 v88, v80
	v_mov_b32_e32 v89, v80
	v_mov_b32_e32 v90, v80
	v_mov_b32_e32 v91, v80
	v_mov_b32_e32 v92, v80
	v_mov_b32_e32 v93, v80
	v_mov_b32_e32 v94, v80
	v_mov_b32_e32 v95, v80
	v_and_b32_e32 v68, 63, v196
	v_lshrrev_b32_e32 v69, 6, v196
	v_lshrrev_b32_e32 v70, 4, v68
	v_and_b32_e32 v71, 15, v68
	v_lshl_add_u32 v64, v69, 3, v70
	v_xor_b32_e32 v65, v71, v70
	v_lshlrev_b32_e32 v64, 9, v64
	v_xor_b32_e32 v66, 4, v65
	v_add_u32_e32 v67, 0x800, v64
	v_lshl_add_u32 v64, v65, 4, v64
	v_lshl_add_u32 v65, v66, 4, v67
	v_bfe_u32 v70, v68, 2, 3
	v_lshl_add_u32 v70, v69, 3, v70
	v_and_b32_e32 v71, 0xfffffff3, v70
	v_and_b32_e32 v66, 4, v70
	v_lshl_or_b32 v71, v66, 1, v71
	v_and_b32_e32 v66, 8, v70
	v_lshrrev_b32_e32 v66, 1, v66
	v_or_b32_e32 v71, v71, v66
	v_lshrrev_b32_e32 v66, 5, v68
	v_and_b32_e32 v67, 3, v68
	v_lshlrev_b32_e32 v66, 6, v66
	v_lshl_add_u32 v66, v67, 4, v66
	v_lshl_add_u32 v66, v71, 9, v66
	v_add_u32_e32 v67, 0x80, v66
	s_waitcnt lgkmcnt(0)
	s_barrier
; #define SBAR() __builtin_amdgcn_sched_barrier(0)
; #define SLOAD(i, k0) do { const unsigned so_ = (unsigned)(k0) * (LDK * 2); \
;     sr_[i].vs0 = BLD8(srV, kvoff, so_); sr_[i].vs1 = BLD8(srV, kvoff + 32u * LDK * 2u, so_); \
;     sr_[i].ks0 = BLD8(srK, kvoff, so_); sr_[i].ks1 = BLD8(srK, kvoff + 32u * LDK * 2u, so_); } while (0)
; __device__ __forceinline__ void finishSM(f32x16& p0, f32x16& p1, float alpha, float& l_reg, bf16x8& pa0, bf16x8& pa1, bf16x8& pa2, bf16x8& pa3) {
;   for (int r = 0; r < 16; ++r) p1[r] = __builtin_amdgcn_exp2f(p1[r]);
;   float ps = 0; for (int r = 0; r < 16; ++r) ps += p0[r]; for (int r = 0; r < 16; ++r) ps += p1[r];
;   { auto rr = __builtin_amdgcn_permlane32_swap(__float_as_uint(ps), __float_as_uint(ps), false, false);
;     ps = __uint_as_float(rr[0]) + __uint_as_float(rr[1]); }
;   l_reg = l_reg * alpha + ps;
;     ...
;   PK4(p0, 0, pa0); PK4(p0, 8, pa1); PK4(p1, 0, pa2); PK4(p1, 8, pa3);
; __device__ __forceinline__ void attn_dense_body(const bf16* Qb, const bf16* __restrict__ Kh, const bf16* __restrict__ Vh,
;                                                 bf16* Ob, int seq, char* lds, const float* __restrict__ qg, const float* __restrict__ rope, int s0) {
;     ...
;     SBAR(); qkt(pB0, pB1, (bf16*)((char*)K_lds + SHM_K), qr, negm, r32, hi);
;     finishSM(pA0, pA1, alA, l_reg, pa0, pa1, pa2, pa3); SBAR();
;     SLOAD(SO, (j + 1) * KVBLK); SBAR();
;     pv_d0(o, vb0, pa0, pa1, pa2, pa3); partialSM<false>(pB0, pB1, m_reg, negm, alB);
.LBB0_96:
	ds_read_b128 v[230:233], v216 offset:57344
	ds_read_b128 v[112:115], v216 offset:49152
	v_add_f32_e32 v178, 0, v245
	v_add_f32_e32 v178, v247, v178
	v_add_f32_e32 v178, v179, v178
	v_add_f32_e32 v178, v246, v178
	s_waitcnt lgkmcnt(0)
	v_mfma_f32_32x32x16_bf16 v[128:143], v[112:115], v[146:149], v[80:95]
	v_add_f32_e32 v178, v180, v178
	v_add_f32_e32 v178, v244, v178
	v_mfma_f32_32x32x16_bf16 v[112:127], v[230:233], v[146:149], v[80:95]
	ds_read_b128 v[230:233], v224 offset:57344
	ds_read_b128 v[248:251], v224 offset:49152
	v_add_f32_e32 v178, v181, v178
	v_add_f32_e32 v178, v243, v178
	v_add_f32_e32 v178, v240, v178
	v_add_f32_e32 v178, v242, v178
	v_add_f32_e32 v178, v239, v178
	v_add_f32_e32 v178, v241, v178
	s_waitcnt lgkmcnt(0)
	v_mfma_f32_32x32x16_bf16 v[128:143], v[248:251], v[150:153], v[128:143]
	v_exp_f32_e32 v96, v96
	v_add_f32_e32 v178, v236, v178
	v_exp_f32_e32 v97, v97
	v_add_f32_e32 v178, v238, v178
	v_exp_f32_e32 v98, v98
	v_add_f32_e32 v178, v235, v178
	v_exp_f32_e32 v99, v99
	v_mfma_f32_32x32x16_bf16 v[112:127], v[230:233], v[150:153], v[112:127]
	ds_read_b128 v[230:233], v223 offset:57344
	ds_read_b128 v[248:251], v223 offset:49152
	v_add_f32_e32 v178, v237, v178
	v_exp_f32_e32 v100, v100
	v_add_f32_e32 v178, v96, v178
	v_exp_f32_e32 v101, v101
	v_add_f32_e32 v178, v97, v178
	v_exp_f32_e32 v102, v102
	s_waitcnt lgkmcnt(0)
	v_mfma_f32_32x32x16_bf16 v[128:143], v[248:251], v[154:157], v[128:143]
	v_add_f32_e32 v178, v98, v178
	v_exp_f32_e32 v103, v103
	v_add_f32_e32 v178, v99, v178
	v_exp_f32_e32 v104, v104
	v_add_f32_e32 v178, v100, v178
	v_exp_f32_e32 v105, v105
	v_add_f32_e32 v178, v101, v178
	v_mfma_f32_32x32x16_bf16 v[112:127], v[230:233], v[154:157], v[112:127]
	ds_read_b128 v[230:233], v221 offset:57344
	ds_read_b128 v[248:251], v221 offset:49152
	v_exp_f32_e32 v106, v106
	v_add_f32_e32 v178, v102, v178
	v_exp_f32_e32 v107, v107
	v_add_f32_e32 v178, v103, v178
	v_exp_f32_e32 v108, v108
	v_add_f32_e32 v178, v104, v178
	s_waitcnt lgkmcnt(0)
	v_mfma_f32_32x32x16_bf16 v[128:143], v[248:251], v[158:161], v[128:143]
	v_exp_f32_e32 v109, v109
	v_add_f32_e32 v178, v105, v178
	v_exp_f32_e32 v110, v110
	v_add_f32_e32 v178, v106, v178
	v_exp_f32_e32 v111, v111
	v_add_f32_e32 v178, v107, v178
	v_add_f32_e32 v178, v108, v178
	v_mfma_f32_32x32x16_bf16 v[112:127], v[230:233], v[158:161], v[112:127]
	ds_read_b128 v[230:233], v222 offset:57344
	ds_read_b128 v[248:251], v222 offset:49152
	v_add_f32_e32 v178, v109, v178
	v_add_f32_e32 v178, v110, v178
	s_waitcnt lgkmcnt(0)
	v_mfma_f32_32x32x16_bf16 v[128:143], v[248:251], v[162:165], v[128:143]
	v_mfma_f32_32x32x16_bf16 v[112:127], v[230:233], v[162:165], v[112:127]
	ds_read_b128 v[230:233], v225 offset:57344
	ds_read_b128 v[248:251], v225 offset:49152
	s_waitcnt lgkmcnt(0)
	v_mfma_f32_32x32x16_bf16 v[128:143], v[248:251], v[166:169], v[128:143]
	v_mfma_f32_32x32x16_bf16 v[112:127], v[230:233], v[166:169], v[112:127]
	ds_read_b128 v[230:233], v226 offset:57344
	ds_read_b128 v[248:251], v226 offset:49152
	s_waitcnt lgkmcnt(0)
	v_mfma_f32_32x32x16_bf16 v[128:143], v[248:251], v[170:173], v[128:143]
	v_mfma_f32_32x32x16_bf16 v[112:127], v[230:233], v[170:173], v[112:127]
	ds_read_b128 v[230:233], v227 offset:57344
	ds_read_b128 v[248:251], v227 offset:49152
	s_waitcnt lgkmcnt(0)
	v_mfma_f32_32x32x16_bf16 v[128:143], v[248:251], v[174:177], v[128:143]
	v_mfma_f32_32x32x16_bf16 v[112:127], v[230:233], v[174:177], v[112:127]
	v_add_f32_e32 v230, v111, v178
	v_mov_b32_e32 v231, v230
	v_cvt_pk_bf16_f32 v178, v245, v247
	v_cvt_pk_bf16_f32 v179, v179, v246
	v_cvt_pk_bf16_f32 v180, v180, v244
	s_nop 1
	v_permlane32_swap_b32_e32 v230, v231
	v_cvt_pk_bf16_f32 v181, v181, v243
	v_permlane32_swap_b32_e32 v178, v180
	v_cvt_pk_bf16_f32 v232, v240, v242
	v_cvt_pk_bf16_f32 v233, v239, v241
	v_cvt_pk_bf16_f32 v234, v236, v238
	v_cvt_pk_bf16_f32 v235, v235, v237
	v_cvt_pk_bf16_f32 v236, v96, v97
	v_cvt_pk_bf16_f32 v237, v98, v99
	v_cvt_pk_bf16_f32 v238, v100, v101
	v_cvt_pk_bf16_f32 v239, v102, v103
	v_cvt_pk_bf16_f32 v240, v104, v105
	v_cvt_pk_bf16_f32 v241, v106, v107
	v_cvt_pk_bf16_f32 v242, v108, v109
	v_cvt_pk_bf16_f32 v243, v110, v111
	v_permlane32_swap_b32_e32 v179, v181
	v_permlane32_swap_b32_e32 v232, v234
	v_permlane32_swap_b32_e32 v233, v235
	v_permlane32_swap_b32_e32 v236, v238
	v_permlane32_swap_b32_e32 v237, v239
	v_permlane32_swap_b32_e32 v240, v242
	v_permlane32_swap_b32_e32 v241, v243
	s_add_i32 s25, s1, 0xffff8000
	s_mov_b32 s58, s90
	s_mov_b32 s59, s91
	s_add_i32 m0, s98, 0x8000
	s_nop 0
	buffer_load_dwordx4 v64, s[56:59], s25 offen lds
	s_add_i32 m0, s98, 0x8400
	s_nop 0
	buffer_load_dwordx4 v65, s[56:59], s25 offen lds
	ds_read_b64_tr_b16 v[244:245], v213 offset:0
	ds_read_b64_tr_b16 v[246:247], v213 offset:0x800
	ds_read_b64_tr_b16 v[248:249], v213 offset:0x1000
	ds_read_b64_tr_b16 v[250:251], v213 offset:0x1800
	ds_read_b64_tr_b16 v[186:187], v213 offset:0x2000
	ds_read_b64_tr_b16 v[188:189], v213 offset:0x2800
	ds_read_b64_tr_b16 v[204:205], v213 offset:0x3000
	ds_read_b64_tr_b16 v[206:207], v213 offset:0x3800
	s_waitcnt lgkmcnt(0)
	s_nop 0
	v_mfma_f32_32x32x16_bf16 v[0:15], v[178:181], v[244:247], v[0:15]
	v_mfma_f32_32x32x16_bf16 v[0:15], v[232:235], v[248:251], v[0:15]
	v_mfma_f32_32x32x16_bf16 v[0:15], v[236:239], v[186:189], v[0:15]
	ds_read_b64_tr_b16 v[186:187], v213 offset:0x200
	ds_read_b64_tr_b16 v[188:189], v213 offset:0xa00
	v_mfma_f32_32x32x16_bf16 v[0:15], v[240:243], v[204:207], v[0:15]
	ds_read_b64_tr_b16 v[204:205], v213 offset:0x1200
	ds_read_b64_tr_b16 v[206:207], v213 offset:0x1a00
	ds_read_b64_tr_b16 v[244:245], v213 offset:0x2200
	ds_read_b64_tr_b16 v[246:247], v213 offset:0x2a00
	ds_read_b64_tr_b16 v[248:249], v213 offset:0x3200
	ds_read_b64_tr_b16 v[250:251], v213 offset:0x3a00
	s_waitcnt lgkmcnt(0)
; #define SBAR() __builtin_amdgcn_sched_barrier(0)
; #define SWRITE(b, i) do { *(bf16x8*)((char*)V_lds + (b) * SHM_V + vst0) = sr_[i].vs0;          \
;     *(bf16x8*)((char*)V_lds + (b) * SHM_V + vst1) = sr_[i].vs1; int kc = sc * 2;               \
;     *(bf16x8*)((char*)K_lds + (b) * SHM_K + KSWZ(sr, kc)) = sr_[i].ks0;                       \
;     *(bf16x8*)((char*)K_lds + (b) * SHM_K + KSWZ(32 + sr, kc)) = sr_[i].ks1; } while (0)
; #define SWAIT() asm volatile("s_waitcnt vmcnt(0)" ::: "memory")
; #define RESC(a) do { if (__any((a) < 1.f)) { if (hi == 0) al_l[r32] = (a); asm volatile("s_waitcnt lgkmcnt(0)" ::: "memory"); \
;     for (int d = 0; d < 4; ++d) for (int r = 0; r < 16; ++r) o[d][r] *= al_l[crow(r, hi)]; } } while (0)
; template <int D0> __device__ __forceinline__ void pv_one(f32x16& od, int vb, bf16x8 pa0, bf16x8 pa1, bf16x8 pa2, bf16x8 pa3) {
;   const s16x4 l0 = tr_read<v_rd_off(D0, 0, 0)>(vb), h0 = tr_read<v_rd_off(D0, 0, 1)>(vb), l1 = tr_read<v_rd_off(D0, 1, 0)>(vb), h1 = tr_read<v_rd_off(D0, 1, 1)>(vb);
;   const s16x4 l2 = tr_read<v_rd_off(D0, 2, 0)>(vb), h2 = tr_read<v_rd_off(D0, 2, 1)>(vb), l3 = tr_read<v_rd_off(D0, 3, 0)>(vb), h3 = tr_read<v_rd_off(D0, 3, 1)>(vb);
;   asm volatile("s_waitcnt lgkmcnt(0)" ::: "memory"); SBAR();
;     ...
;   od = __builtin_amdgcn_mfma_f32_32x32x16_bf16(pa0, PK(l0, h0), od, 0, 0, 0);
;   od = __builtin_amdgcn_mfma_f32_32x32x16_bf16(pa1, PK(l1, h1), od, 0, 0, 0);
;   od = __builtin_amdgcn_mfma_f32_32x32x16_bf16(pa2, PK(l2, h2), od, 0, 0, 0);
;   od = __builtin_amdgcn_mfma_f32_32x32x16_bf16(pa3, PK(l3, h3), od, 0, 0, 0);
;     ...
; }
; __device__ __forceinline__ void pv_d0(f32x16* o, int vb, bf16x8 pa0, bf16x8 pa1, bf16x8 pa2, bf16x8 pa3) {
;   pv_one<0>(o[0], vb, pa0, pa1, pa2, pa3); pv_one<1>(o[1], vb, pa0, pa1, pa2, pa3); pv_one<2>(o[2], vb, pa0, pa1, pa2, pa3); pv_one<3>(o[3], vb, pa0, pa1, pa2, pa3);
; __device__ __forceinline__ void attn_dense_body(const bf16* Qb, const bf16* __restrict__ Kh, const bf16* __restrict__ Vh,
;                                                 bf16* Ob, int seq, char* lds, const float* __restrict__ qg, const float* __restrict__ rope, int s0) {
;     ...
;     pv_d0(o, vb0, pa0, pa1, pa2, pa3); partialSM<false>(pB0, pB1, m_reg, negm, alB);
;     __syncthreads(); SWAIT(); SWRITE(0, SE);
;     RESC(alB); __syncthreads();
	v_mfma_f32_32x32x16_bf16 v[32:47], v[178:181], v[186:189], v[32:47]
	ds_read_b64_tr_b16 v[186:187], v213 offset:0x400
	ds_read_b64_tr_b16 v[188:189], v213 offset:0xc00
	v_mfma_f32_32x32x16_bf16 v[32:47], v[232:235], v[204:207], v[32:47]
	ds_read_b64_tr_b16 v[204:205], v213 offset:0x1400
	ds_read_b64_tr_b16 v[206:207], v213 offset:0x1c00
	v_mfma_f32_32x32x16_bf16 v[32:47], v[236:239], v[244:247], v[32:47]
	ds_read_b64_tr_b16 v[244:245], v213 offset:0x2400
	ds_read_b64_tr_b16 v[246:247], v213 offset:0x2c00
	v_mfma_f32_32x32x16_bf16 v[32:47], v[240:243], v[248:251], v[32:47]
	ds_read_b64_tr_b16 v[248:249], v213 offset:0x3400
	ds_read_b64_tr_b16 v[250:251], v213 offset:0x3c00
	s_waitcnt lgkmcnt(0)
	v_mfma_f32_32x32x16_bf16 v[16:31], v[178:181], v[186:189], v[16:31]
	ds_read_b64_tr_b16 v[186:187], v213 offset:0x600
	ds_read_b64_tr_b16 v[188:189], v213 offset:0xe00
	v_mfma_f32_32x32x16_bf16 v[16:31], v[232:235], v[204:207], v[16:31]
	ds_read_b64_tr_b16 v[204:205], v213 offset:0x1600
	ds_read_b64_tr_b16 v[206:207], v213 offset:0x1e00
	v_mfma_f32_32x32x16_bf16 v[16:31], v[236:239], v[244:247], v[16:31]
	ds_read_b64_tr_b16 v[244:245], v213 offset:0x2600
	ds_read_b64_tr_b16 v[246:247], v213 offset:0x2e00
	v_mfma_f32_32x32x16_bf16 v[16:31], v[240:243], v[248:251], v[16:31]
	ds_read_b64_tr_b16 v[248:249], v213 offset:0x3600
	ds_read_b64_tr_b16 v[250:251], v213 offset:0x3e00
	s_waitcnt lgkmcnt(0)
	v_mfma_f32_32x32x16_bf16 v[48:63], v[178:181], v[186:189], v[48:63]
	v_max_f32_e32 v178, v129, v129
	v_max_f32_e32 v179, v128, v128
	v_max_f32_e32 v178, v179, v178
	v_max3_f32 v178, v178, v130, v131
	v_max3_f32 v178, v178, v132, v133
	v_max3_f32 v178, v178, v134, v135
	v_max3_f32 v178, v178, v136, v137
	v_mfma_f32_32x32x16_bf16 v[48:63], v[232:235], v[204:207], v[48:63]
	v_max3_f32 v178, v178, v138, v139
	v_max3_f32 v178, v178, v140, v141
	v_max3_f32 v178, v178, v142, v143
	v_max3_f32 v178, v178, v112, v113
	v_max3_f32 v178, v178, v114, v115
	v_max3_f32 v178, v178, v116, v117
	v_max3_f32 v178, v178, v118, v119
	v_mfma_f32_32x32x16_bf16 v[48:63], v[236:239], v[244:247], v[48:63]
	v_max3_f32 v178, v178, v120, v121
	v_max3_f32 v178, v178, v122, v123
	v_max3_f32 v178, v178, v124, v125
	v_max3_f32 v178, v178, v126, v127
	v_mov_b32_e32 v179, v178
	s_nop 1
	v_permlane32_swap_b32_e32 v178, v179
	v_mfma_f32_32x32x16_bf16 v[48:63], v[240:243], v[248:251], v[48:63]
	v_max_f32_e32 v179, v179, v179
	v_max_f32_e32 v178, v178, v178
	v_max_f32_e32 v178, v178, v179
	v_cmp_ge_f32_e32 vcc, s5, v178
	s_cmp_eq_u64 vcc, exec
	s_cbranch_scc0 .LBB0_109
	v_mov_b32_e32 v232, 1.0
.LBB0_98:
	s_barrier
	v_cmp_gt_f32_e32 vcc, 1.0, v232
	s_mov_b32 m0, s98
	s_nop 0
	buffer_load_dwordx4 v66, s[88:91], s25 offen lds
	s_add_i32 m0, s98, 0x400
	s_nop 0
	buffer_load_dwordx4 v67, s[88:91], s25 offen lds
	s_cbranch_vccz .LBB0_102
	s_and_saveexec_b64 s[58:59], s[52:53]
	ds_write_b32 v211, v232 offset:128
	s_or_b64 exec, exec, s[58:59]
	s_waitcnt lgkmcnt(0)
	v_add_u32_e32 v108, v210, v194
	ds_read_b128 v[96:99], v108 offset:224
	ds_read_b128 v[100:103], v108 offset:192
	ds_read_b128 v[104:107], v108 offset:160
	ds_read_b128 v[108:111], v108 offset:128
	s_waitcnt lgkmcnt(3)
	v_pk_mul_f32 v[12:13], v[12:13], v[96:97]
	s_waitcnt lgkmcnt(2)
	v_pk_mul_f32 v[8:9], v[8:9], v[100:101]
	s_waitcnt lgkmcnt(1)
	v_pk_mul_f32 v[4:5], v[4:5], v[104:105]
	v_pk_mul_f32 v[14:15], v[14:15], v[98:99]
	v_pk_mul_f32 v[10:11], v[10:11], v[102:103]
	v_pk_mul_f32 v[6:7], v[6:7], v[106:107]
	s_waitcnt lgkmcnt(0)
	v_pk_mul_f32 v[2:3], v[2:3], v[110:111]
	v_pk_mul_f32 v[0:1], v[0:1], v[108:109]
	v_pk_mul_f32 v[44:45], v[44:45], v[96:97]
	v_pk_mul_f32 v[40:41], v[40:41], v[100:101]
	v_pk_mul_f32 v[36:37], v[36:37], v[104:105]
	v_pk_mul_f32 v[46:47], v[46:47], v[98:99]
	v_pk_mul_f32 v[42:43], v[42:43], v[102:103]
	v_pk_mul_f32 v[38:39], v[38:39], v[106:107]
	v_pk_mul_f32 v[34:35], v[34:35], v[110:111]
	v_pk_mul_f32 v[32:33], v[32:33], v[108:109]
	v_pk_mul_f32 v[28:29], v[28:29], v[96:97]
	v_pk_mul_f32 v[24:25], v[24:25], v[100:101]
	v_pk_mul_f32 v[20:21], v[20:21], v[104:105]
	v_pk_mul_f32 v[30:31], v[30:31], v[98:99]
	v_pk_mul_f32 v[26:27], v[26:27], v[102:103]
	v_pk_mul_f32 v[22:23], v[22:23], v[106:107]
	v_pk_mul_f32 v[18:19], v[18:19], v[110:111]
	v_pk_mul_f32 v[16:17], v[16:17], v[108:109]
	v_pk_mul_f32 v[60:61], v[60:61], v[96:97]
	v_pk_mul_f32 v[56:57], v[56:57], v[100:101]
	v_pk_mul_f32 v[52:53], v[52:53], v[104:105]
	v_pk_mul_f32 v[62:63], v[62:63], v[98:99]
	v_pk_mul_f32 v[58:59], v[58:59], v[102:103]
	v_pk_mul_f32 v[54:55], v[54:55], v[106:107]
	v_pk_mul_f32 v[50:51], v[50:51], v[110:111]
	v_pk_mul_f32 v[48:49], v[48:49], v[108:109]
; #define SBAR() __builtin_amdgcn_sched_barrier(0)
; #define SLOAD(i, k0) do { const unsigned so_ = (unsigned)(k0) * (LDK * 2); \
;     sr_[i].vs0 = BLD8(srV, kvoff, so_); sr_[i].vs1 = BLD8(srV, kvoff + 32u * LDK * 2u, so_); \
;     sr_[i].ks0 = BLD8(srK, kvoff, so_); sr_[i].ks1 = BLD8(srK, kvoff + 32u * LDK * 2u, so_); } while (0)
; #define RESC(a) do { if (__any((a) < 1.f)) { if (hi == 0) al_l[r32] = (a); asm volatile("s_waitcnt lgkmcnt(0)" ::: "memory"); \
;     for (int d = 0; d < 4; ++d) for (int r = 0; r < 16; ++r) o[d][r] *= al_l[crow(r, hi)]; } } while (0)
; __device__ __forceinline__ void qkt(f32x16& p0, f32x16& p1, const bf16* Ks, const bf16x8* qr, const f32x16& negm, int r32, int hi) {
; #pragma unroll
;   for (int d0 = 0; d0 < 8; ++d0) { int cb = (d0 * 16 + hi * 8) * 2;
;     bf16x8 b0 = *reinterpret_cast<const bf16x8*>((const char*)Ks + KSWZ(r32, cb));
;     bf16x8 b1 = *reinterpret_cast<const bf16x8*>((const char*)Ks + KSWZ(32 + r32, cb));
;     if (d0 == 0) { p0 = __builtin_amdgcn_mfma_f32_32x32x16_bf16(b0, qr[0], negm, 0, 0, 0); p1 = __builtin_amdgcn_mfma_f32_32x32x16_bf16(b1, qr[0], negm, 0, 0, 0); }
;     else { p0 = __builtin_amdgcn_mfma_f32_32x32x16_bf16(b0, qr[d0], p0, 0, 0, 0); p1 = __builtin_amdgcn_mfma_f32_32x32x16_bf16(b1, qr[d0], p1, 0, 0, 0); } }
; }
; __device__ __forceinline__ void attn_dense_body(const bf16* Qb, const bf16* __restrict__ Kh, const bf16* __restrict__ Vh,
;                                                 bf16* Ob, int seq, char* lds, const float* __restrict__ qg, const float* __restrict__ rope, int s0) {
;     ...
;     RESC(alB); __syncthreads();
;     SBAR(); qkt(pA0, pA1, K_lds, qr, negm, r32, hi);
;     finishSM(pB0, pB1, alB, l_reg, pa0, pa1, pa2, pa3); SBAR();
;     SLOAD(SE, (j + 2) * KVBLK); SBAR();
;     pv_d0(o, vb0 + (int)SHM_V, pa0, pa1, pa2, pa3); partialSM<false>(pA0, pA1, m_reg, negm, alA);
.LBB0_102:
	v_exp_f32_e32 v178, v128
	v_exp_f32_e32 v179, v130
	v_exp_f32_e32 v246, v129
	v_exp_f32_e32 v245, v131
	v_exp_f32_e32 v180, v132
	v_exp_f32_e32 v244, v133
	v_exp_f32_e32 v181, v134
	v_exp_f32_e32 v243, v135
	v_exp_f32_e32 v240, v136
	v_exp_f32_e32 v242, v137
	v_exp_f32_e32 v239, v138
	v_exp_f32_e32 v241, v139
	v_exp_f32_e32 v236, v140
	v_exp_f32_e32 v238, v141
	v_exp_f32_e32 v235, v142
	v_exp_f32_e32 v237, v143
	s_waitcnt vmcnt(2)
	s_waitcnt lgkmcnt(0)
	s_barrier
	ds_read_b128 v[186:189], v216 offset:40960
	ds_read_b128 v[96:99], v216 offset:32768
	v_add_f32_e32 v182, 0, v178
	v_add_f32_e32 v182, v246, v182
	v_add_f32_e32 v182, v179, v182
	v_add_f32_e32 v182, v245, v182
	s_waitcnt lgkmcnt(0)
	v_mfma_f32_32x32x16_bf16 v[128:143], v[96:99], v[146:149], v[80:95]
	v_add_f32_e32 v182, v180, v182
	v_add_f32_e32 v182, v244, v182
	v_add_f32_e32 v182, v181, v182
	v_add_f32_e32 v182, v243, v182
	v_add_f32_e32 v182, v240, v182
	v_add_f32_e32 v182, v242, v182
	v_add_f32_e32 v182, v239, v182
	v_mfma_f32_32x32x16_bf16 v[96:111], v[186:189], v[146:149], v[80:95]
	ds_read_b128 v[186:189], v224 offset:40960
	ds_read_b128 v[204:207], v224 offset:32768
	v_add_f32_e32 v182, v241, v182
	v_exp_f32_e32 v112, v112
	v_add_f32_e32 v182, v236, v182
	v_exp_f32_e32 v113, v113
	v_add_f32_e32 v182, v238, v182
	v_exp_f32_e32 v114, v114
	s_waitcnt lgkmcnt(0)
	v_mfma_f32_32x32x16_bf16 v[128:143], v[204:207], v[150:153], v[128:143]
	v_add_f32_e32 v182, v235, v182
	v_exp_f32_e32 v115, v115
	v_add_f32_e32 v182, v237, v182
	v_exp_f32_e32 v116, v116
	v_add_f32_e32 v182, v112, v182
	v_exp_f32_e32 v117, v117
	v_add_f32_e32 v182, v113, v182
	v_mfma_f32_32x32x16_bf16 v[96:111], v[186:189], v[150:153], v[96:111]
	ds_read_b128 v[186:189], v223 offset:40960
	ds_read_b128 v[204:207], v223 offset:32768
	v_exp_f32_e32 v118, v118
	v_add_f32_e32 v182, v114, v182
	v_exp_f32_e32 v119, v119
	v_add_f32_e32 v182, v115, v182
	v_exp_f32_e32 v120, v120
	v_add_f32_e32 v182, v116, v182
	s_waitcnt lgkmcnt(0)
	v_mfma_f32_32x32x16_bf16 v[128:143], v[204:207], v[154:157], v[128:143]
	v_exp_f32_e32 v121, v121
	v_add_f32_e32 v182, v117, v182
	v_exp_f32_e32 v122, v122
	v_add_f32_e32 v182, v118, v182
	v_exp_f32_e32 v123, v123
	v_add_f32_e32 v182, v119, v182
	v_exp_f32_e32 v124, v124
	v_mfma_f32_32x32x16_bf16 v[96:111], v[186:189], v[154:157], v[96:111]
	ds_read_b128 v[186:189], v221 offset:40960
	ds_read_b128 v[204:207], v221 offset:32768
	v_add_f32_e32 v182, v120, v182
	v_exp_f32_e32 v125, v125
	v_add_f32_e32 v182, v121, v182
	v_exp_f32_e32 v126, v126
	v_add_f32_e32 v182, v122, v182
	v_exp_f32_e32 v127, v127
	s_waitcnt lgkmcnt(0)
	v_mfma_f32_32x32x16_bf16 v[128:143], v[204:207], v[158:161], v[128:143]
	v_add_f32_e32 v182, v123, v182
	v_add_f32_e32 v182, v124, v182
	v_add_f32_e32 v182, v125, v182
	v_add_f32_e32 v182, v126, v182
	v_add_f32_e32 v233, v127, v182
	v_mov_b32_e32 v234, v233
	s_nop 1
	v_permlane32_swap_b32_e32 v233, v234
	v_mfma_f32_32x32x16_bf16 v[96:111], v[186:189], v[158:161], v[96:111]
	ds_read_b128 v[186:189], v222 offset:40960
	ds_read_b128 v[204:207], v222 offset:32768
	s_waitcnt lgkmcnt(0)
	v_mfma_f32_32x32x16_bf16 v[128:143], v[204:207], v[162:165], v[128:143]
	v_mfma_f32_32x32x16_bf16 v[96:111], v[186:189], v[162:165], v[96:111]
	ds_read_b128 v[186:189], v225 offset:40960
	ds_read_b128 v[204:207], v225 offset:32768
	s_waitcnt lgkmcnt(0)
	v_mfma_f32_32x32x16_bf16 v[128:143], v[204:207], v[166:169], v[128:143]
	v_mfma_f32_32x32x16_bf16 v[96:111], v[186:189], v[166:169], v[96:111]
	ds_read_b128 v[186:189], v226 offset:40960
	ds_read_b128 v[204:207], v226 offset:32768
	s_waitcnt lgkmcnt(0)
	v_mfma_f32_32x32x16_bf16 v[128:143], v[204:207], v[170:173], v[128:143]
	v_mfma_f32_32x32x16_bf16 v[96:111], v[186:189], v[170:173], v[96:111]
	ds_read_b128 v[186:189], v227 offset:40960
	ds_read_b128 v[204:207], v227 offset:32768
	v_cvt_pk_bf16_f32 v178, v178, v246
	v_cvt_pk_bf16_f32 v179, v179, v245
	v_cvt_pk_bf16_f32 v180, v180, v244
	v_cvt_pk_bf16_f32 v181, v181, v243
	s_nop 0
	v_permlane32_swap_b32_e32 v178, v180
	s_waitcnt lgkmcnt(0)
	v_mfma_f32_32x32x16_bf16 v[128:143], v[204:207], v[174:177], v[128:143]
	v_permlane32_swap_b32_e32 v179, v181
	v_mfma_f32_32x32x16_bf16 v[96:111], v[186:189], v[174:177], v[96:111]
	v_cvt_pk_bf16_f32 v186, v240, v242
	v_cvt_pk_bf16_f32 v187, v239, v241
	v_cvt_pk_bf16_f32 v188, v236, v238
	v_cvt_pk_bf16_f32 v189, v235, v237
	v_cvt_pk_bf16_f32 v204, v112, v113
	v_cvt_pk_bf16_f32 v205, v114, v115
	v_cvt_pk_bf16_f32 v206, v116, v117
	v_cvt_pk_bf16_f32 v207, v118, v119
	v_cvt_pk_bf16_f32 v236, v120, v121
	v_cvt_pk_bf16_f32 v237, v122, v123
	v_cvt_pk_bf16_f32 v238, v124, v125
	v_cvt_pk_bf16_f32 v239, v126, v127
	s_nop 0
	v_permlane32_swap_b32_e32 v186, v188
	v_permlane32_swap_b32_e32 v187, v189
	v_permlane32_swap_b32_e32 v204, v206
	v_permlane32_swap_b32_e32 v205, v207
	v_permlane32_swap_b32_e32 v236, v238
	v_permlane32_swap_b32_e32 v237, v239
	s_mov_b32 s58, s90
	s_mov_b32 s59, s91
	s_add_i32 m0, s98, 0xc000
	s_nop 0
	buffer_load_dwordx4 v64, s[56:59], s1 offen lds
	s_add_i32 m0, s98, 0xc400
	s_nop 0
	buffer_load_dwordx4 v65, s[56:59], s1 offen lds
	ds_read_b64_tr_b16 v[240:241], v212 offset:0
	ds_read_b64_tr_b16 v[242:243], v212 offset:0x800
	ds_read_b64_tr_b16 v[244:245], v212 offset:0x1000
	ds_read_b64_tr_b16 v[246:247], v212 offset:0x1800
	ds_read_b64_tr_b16 v[248:249], v212 offset:0x2000
	ds_read_b64_tr_b16 v[250:251], v212 offset:0x2800
	ds_read_b64_tr_b16 v[182:183], v212 offset:0x3000
	ds_read_b64_tr_b16 v[184:185], v212 offset:0x3800
	s_waitcnt lgkmcnt(0)
; #define SBAR() __builtin_amdgcn_sched_barrier(0)
; #define SWRITE(b, i) do { *(bf16x8*)((char*)V_lds + (b) * SHM_V + vst0) = sr_[i].vs0;          \
;     *(bf16x8*)((char*)V_lds + (b) * SHM_V + vst1) = sr_[i].vs1; int kc = sc * 2;               \
;     *(bf16x8*)((char*)K_lds + (b) * SHM_K + KSWZ(sr, kc)) = sr_[i].ks0;                       \
;     *(bf16x8*)((char*)K_lds + (b) * SHM_K + KSWZ(32 + sr, kc)) = sr_[i].ks1; } while (0)
; #define SWAIT() asm volatile("s_waitcnt vmcnt(0)" ::: "memory")
; #define RESC(a) do { if (__any((a) < 1.f)) { if (hi == 0) al_l[r32] = (a); asm volatile("s_waitcnt lgkmcnt(0)" ::: "memory"); \
;     for (int d = 0; d < 4; ++d) for (int r = 0; r < 16; ++r) o[d][r] *= al_l[crow(r, hi)]; } } while (0)
; template <int D0> __device__ __forceinline__ void pv_one(f32x16& od, int vb, bf16x8 pa0, bf16x8 pa1, bf16x8 pa2, bf16x8 pa3) {
;   const s16x4 l0 = tr_read<v_rd_off(D0, 0, 0)>(vb), h0 = tr_read<v_rd_off(D0, 0, 1)>(vb), l1 = tr_read<v_rd_off(D0, 1, 0)>(vb), h1 = tr_read<v_rd_off(D0, 1, 1)>(vb);
;   const s16x4 l2 = tr_read<v_rd_off(D0, 2, 0)>(vb), h2 = tr_read<v_rd_off(D0, 2, 1)>(vb), l3 = tr_read<v_rd_off(D0, 3, 0)>(vb), h3 = tr_read<v_rd_off(D0, 3, 1)>(vb);
;   asm volatile("s_waitcnt lgkmcnt(0)" ::: "memory"); SBAR();
;     ...
;   od = __builtin_amdgcn_mfma_f32_32x32x16_bf16(pa0, PK(l0, h0), od, 0, 0, 0);
;   od = __builtin_amdgcn_mfma_f32_32x32x16_bf16(pa1, PK(l1, h1), od, 0, 0, 0);
;   od = __builtin_amdgcn_mfma_f32_32x32x16_bf16(pa2, PK(l2, h2), od, 0, 0, 0);
;   od = __builtin_amdgcn_mfma_f32_32x32x16_bf16(pa3, PK(l3, h3), od, 0, 0, 0);
;     ...
; }
; __device__ __forceinline__ void pv_d0(f32x16* o, int vb, bf16x8 pa0, bf16x8 pa1, bf16x8 pa2, bf16x8 pa3) {
;   pv_one<0>(o[0], vb, pa0, pa1, pa2, pa3); pv_one<1>(o[1], vb, pa0, pa1, pa2, pa3); pv_one<2>(o[2], vb, pa0, pa1, pa2, pa3); pv_one<3>(o[3], vb, pa0, pa1, pa2, pa3);
; __device__ __forceinline__ void attn_dense_body(const bf16* Qb, const bf16* __restrict__ Kh, const bf16* __restrict__ Vh,
;                                                 bf16* Ob, int seq, char* lds, const float* __restrict__ qg, const float* __restrict__ rope, int s0) {
;     ...
;     pv_d0(o, vb0 + (int)SHM_V, pa0, pa1, pa2, pa3); partialSM<false>(pA0, pA1, m_reg, negm, alA);
;     __syncthreads(); SWAIT(); SWRITE(1, SO);
;     RESC(alA); __syncthreads();
	s_nop 0
	v_mfma_f32_32x32x16_bf16 v[0:15], v[178:181], v[240:243], v[0:15]
	v_mfma_f32_32x32x16_bf16 v[0:15], v[186:189], v[244:247], v[0:15]
	v_mfma_f32_32x32x16_bf16 v[0:15], v[204:207], v[248:251], v[0:15]
	v_mfma_f32_32x32x16_bf16 v[0:15], v[236:239], v[182:185], v[0:15]
	ds_read_b64_tr_b16 v[182:183], v212 offset:0x200
	ds_read_b64_tr_b16 v[184:185], v212 offset:0xa00
	ds_read_b64_tr_b16 v[240:241], v212 offset:0x1200
	ds_read_b64_tr_b16 v[242:243], v212 offset:0x1a00
	ds_read_b64_tr_b16 v[244:245], v212 offset:0x2200
	ds_read_b64_tr_b16 v[246:247], v212 offset:0x2a00
	ds_read_b64_tr_b16 v[248:249], v212 offset:0x3200
	ds_read_b64_tr_b16 v[250:251], v212 offset:0x3a00
	s_waitcnt lgkmcnt(0)
	s_nop 0
	v_mfma_f32_32x32x16_bf16 v[32:47], v[178:181], v[182:185], v[32:47]
	ds_read_b64_tr_b16 v[182:183], v212 offset:0x400
	ds_read_b64_tr_b16 v[184:185], v212 offset:0xc00
	v_mfma_f32_32x32x16_bf16 v[32:47], v[186:189], v[240:243], v[32:47]
	ds_read_b64_tr_b16 v[240:241], v212 offset:0x1400
	ds_read_b64_tr_b16 v[242:243], v212 offset:0x1c00
	v_mfma_f32_32x32x16_bf16 v[32:47], v[204:207], v[244:247], v[32:47]
	ds_read_b64_tr_b16 v[244:245], v212 offset:0x2400
	ds_read_b64_tr_b16 v[246:247], v212 offset:0x2c00
	v_mfma_f32_32x32x16_bf16 v[32:47], v[236:239], v[248:251], v[32:47]
	ds_read_b64_tr_b16 v[248:249], v212 offset:0x3400
	ds_read_b64_tr_b16 v[250:251], v212 offset:0x3c00
	s_waitcnt lgkmcnt(0)
	v_mfma_f32_32x32x16_bf16 v[16:31], v[178:181], v[182:185], v[16:31]
	ds_read_b64_tr_b16 v[182:183], v212 offset:0x600
	ds_read_b64_tr_b16 v[184:185], v212 offset:0xe00
	v_mfma_f32_32x32x16_bf16 v[16:31], v[186:189], v[240:243], v[16:31]
	ds_read_b64_tr_b16 v[240:241], v212 offset:0x1600
	ds_read_b64_tr_b16 v[242:243], v212 offset:0x1e00
	v_mfma_f32_32x32x16_bf16 v[16:31], v[204:207], v[244:247], v[16:31]
	ds_read_b64_tr_b16 v[244:245], v212 offset:0x2600
	ds_read_b64_tr_b16 v[246:247], v212 offset:0x2e00
	v_mfma_f32_32x32x16_bf16 v[16:31], v[236:239], v[248:251], v[16:31]
	ds_read_b64_tr_b16 v[248:249], v212 offset:0x3600
	ds_read_b64_tr_b16 v[250:251], v212 offset:0x3e00
	s_waitcnt lgkmcnt(0)
	v_mfma_f32_32x32x16_bf16 v[48:63], v[178:181], v[182:185], v[48:63]
	v_max_f32_e32 v178, v129, v129
	v_max_f32_e32 v179, v128, v128
	v_max_f32_e32 v178, v179, v178
	v_max3_f32 v178, v178, v130, v131
	v_max3_f32 v178, v178, v132, v133
	v_max3_f32 v178, v178, v134, v135
	v_max3_f32 v178, v178, v136, v137
	v_mfma_f32_32x32x16_bf16 v[48:63], v[186:189], v[240:243], v[48:63]
	v_max3_f32 v178, v178, v138, v139
	v_max3_f32 v178, v178, v140, v141
	v_max3_f32 v178, v178, v142, v143
	v_max3_f32 v178, v178, v96, v97
	v_max3_f32 v178, v178, v98, v99
	v_max3_f32 v178, v178, v100, v101
	v_max3_f32 v178, v178, v102, v103
	v_mfma_f32_32x32x16_bf16 v[48:63], v[204:207], v[244:247], v[48:63]
	v_max3_f32 v178, v178, v104, v105
	v_max3_f32 v178, v178, v106, v107
	v_max3_f32 v178, v178, v108, v109
	v_max3_f32 v178, v178, v110, v111
	v_mov_b32_e32 v179, v178
	s_nop 1
	v_permlane32_swap_b32_e32 v178, v179
	v_mfma_f32_32x32x16_bf16 v[48:63], v[236:239], v[248:251], v[48:63]
	v_max_f32_e32 v179, v179, v179
	v_max_f32_e32 v178, v178, v178
	v_max_f32_e32 v179, v178, v179
	v_cmp_ge_f32_e32 vcc, s5, v179
	s_cmp_eq_u64 vcc, exec
	v_mov_b32_e32 v178, 1.0
	s_cbranch_scc0 .LBB0_110
.LBB0_103:
	s_barrier
	v_cmp_gt_f32_e32 vcc, 1.0, v178
	s_add_i32 m0, s98, 0x4000
	s_nop 0
	buffer_load_dwordx4 v66, s[88:91], s1 offen lds
	s_add_i32 m0, s98, 0x4400
	s_nop 0
	buffer_load_dwordx4 v67, s[88:91], s1 offen lds
	s_cbranch_vccz .LBB0_107
	s_and_saveexec_b64 s[58:59], s[52:53]
	ds_write_b32 v211, v178 offset:128
	s_or_b64 exec, exec, s[58:59]
	s_waitcnt lgkmcnt(0)
	v_add_u32_e32 v124, v210, v194
	ds_read_b128 v[112:115], v124 offset:224
	ds_read_b128 v[116:119], v124 offset:192
	ds_read_b128 v[120:123], v124 offset:160
	ds_read_b128 v[124:127], v124 offset:128
	s_waitcnt lgkmcnt(3)
	v_pk_mul_f32 v[12:13], v[12:13], v[112:113]
	s_waitcnt lgkmcnt(2)
	v_pk_mul_f32 v[8:9], v[8:9], v[116:117]
	s_waitcnt lgkmcnt(1)
	v_pk_mul_f32 v[4:5], v[4:5], v[120:121]
	v_pk_mul_f32 v[14:15], v[14:15], v[114:115]
	v_pk_mul_f32 v[10:11], v[10:11], v[118:119]
	v_pk_mul_f32 v[6:7], v[6:7], v[122:123]
	s_waitcnt lgkmcnt(0)
	v_pk_mul_f32 v[2:3], v[2:3], v[126:127]
	v_pk_mul_f32 v[0:1], v[0:1], v[124:125]
	v_pk_mul_f32 v[44:45], v[44:45], v[112:113]
	v_pk_mul_f32 v[40:41], v[40:41], v[116:117]
	v_pk_mul_f32 v[36:37], v[36:37], v[120:121]
	v_pk_mul_f32 v[46:47], v[46:47], v[114:115]
	v_pk_mul_f32 v[42:43], v[42:43], v[118:119]
	v_pk_mul_f32 v[38:39], v[38:39], v[122:123]
	v_pk_mul_f32 v[34:35], v[34:35], v[126:127]
	v_pk_mul_f32 v[32:33], v[32:33], v[124:125]
	v_pk_mul_f32 v[28:29], v[28:29], v[112:113]
	v_pk_mul_f32 v[24:25], v[24:25], v[116:117]
	v_pk_mul_f32 v[20:21], v[20:21], v[120:121]
	v_pk_mul_f32 v[30:31], v[30:31], v[114:115]
	v_pk_mul_f32 v[26:27], v[26:27], v[118:119]
	v_pk_mul_f32 v[22:23], v[22:23], v[122:123]
	v_pk_mul_f32 v[18:19], v[18:19], v[126:127]
	v_pk_mul_f32 v[16:17], v[16:17], v[124:125]
	v_pk_mul_f32 v[60:61], v[60:61], v[112:113]
	v_pk_mul_f32 v[56:57], v[56:57], v[116:117]
	v_pk_mul_f32 v[52:53], v[52:53], v[120:121]
	v_pk_mul_f32 v[62:63], v[62:63], v[114:115]
	v_pk_mul_f32 v[58:59], v[58:59], v[118:119]
	v_pk_mul_f32 v[54:55], v[54:55], v[122:123]
	v_pk_mul_f32 v[50:51], v[50:51], v[126:127]
	v_pk_mul_f32 v[48:49], v[48:49], v[124:125]
; #define RESC(a) do { if (__any((a) < 1.f)) { if (hi == 0) al_l[r32] = (a); asm volatile("s_waitcnt lgkmcnt(0)" ::: "memory"); \
;     for (int d = 0; d < 4; ++d) for (int r = 0; r < 16; ++r) o[d][r] *= al_l[crow(r, hi)]; } } while (0)
; template <bool FIRST>
; __device__ __forceinline__ void partialSM(f32x16& p0, f32x16& p1, float& m_reg, f32x16& negm, float& alpha) {
;     ...
;   if (!FIRST && __builtin_expect(__all(pmax <= THRL), 1)) { alpha = 1.f; }
;   else {
;     const float d = FIRST ? pmax : fmaxf(pmax, 0.f);
;     alpha = FIRST ? 1.f : __builtin_amdgcn_exp2f(-d);
;     m_reg += d;
;     for (int r = 0; r < 16; ++r) p0[r] -= d; for (int r = 0; r < 16; ++r) p1[r] -= d;
;     const float nm = -m_reg; for (int r = 0; r < 16; ++r) negm[r] = nm;
;   }
; __device__ __forceinline__ void attn_dense_body(const bf16* Qb, const bf16* __restrict__ Kh, const bf16* __restrict__ Vh,
;                                                 bf16* Ob, int seq, char* lds, const float* __restrict__ qg, const float* __restrict__ rope, int s0) {
;     ...
;     RESC(alA); __syncthreads();
;   }
.LBB0_107:
	v_exp_f32_e32 v245, v128
	v_exp_f32_e32 v247, v129
	v_exp_f32_e32 v179, v130
	v_exp_f32_e32 v246, v131
	v_exp_f32_e32 v180, v132
	v_exp_f32_e32 v244, v133
	v_exp_f32_e32 v181, v134
	v_exp_f32_e32 v243, v135
	v_exp_f32_e32 v240, v136
	v_exp_f32_e32 v242, v137
	v_exp_f32_e32 v239, v138
	v_exp_f32_e32 v241, v139
	v_exp_f32_e32 v236, v140
	v_exp_f32_e32 v238, v141
	v_exp_f32_e32 v235, v142
	v_exp_f32_e32 v237, v143
	v_add_f32_e32 v112, v230, v231
	v_fmac_f32_e32 v112, v228, v193
	v_add_f32_e32 v193, v233, v234
	s_add_i32 s0, s0, 2
	s_add_i32 s1, s1, 0x10000
	v_fmac_f32_e32 v193, v112, v232
	s_cmp_gt_u32 s0, 60
	s_waitcnt vmcnt(2)
	s_waitcnt lgkmcnt(0)
	s_barrier
	s_cbranch_scc1 .LBB0_111
	v_mov_b32_e32 v228, v178
	s_branch .LBB0_96
.LBB0_109:
	v_max_f32_e32 v68, v178, v178
	v_max_f32_e32 v68, 0, v68
	v_exp_f32_e64 v232, -v68
	v_add_f32_e32 v229, v229, v68
	v_pk_add_f32 v[128:129], v[128:129], v[68:69] op_sel_hi:[1,0] neg_lo:[0,1] neg_hi:[0,1]
	v_pk_add_f32 v[130:131], v[130:131], v[68:69] op_sel_hi:[1,0] neg_lo:[0,1] neg_hi:[0,1]
	v_pk_add_f32 v[132:133], v[132:133], v[68:69] op_sel_hi:[1,0] neg_lo:[0,1] neg_hi:[0,1]
	v_pk_add_f32 v[134:135], v[134:135], v[68:69] op_sel_hi:[1,0] neg_lo:[0,1] neg_hi:[0,1]
	v_pk_add_f32 v[136:137], v[136:137], v[68:69] op_sel_hi:[1,0] neg_lo:[0,1] neg_hi:[0,1]
	v_pk_add_f32 v[138:139], v[138:139], v[68:69] op_sel_hi:[1,0] neg_lo:[0,1] neg_hi:[0,1]
	v_pk_add_f32 v[140:141], v[140:141], v[68:69] op_sel_hi:[1,0] neg_lo:[0,1] neg_hi:[0,1]
	v_pk_add_f32 v[142:143], v[142:143], v[68:69] op_sel_hi:[1,0] neg_lo:[0,1] neg_hi:[0,1]
	v_sub_f32_e32 v127, v127, v68
	v_sub_f32_e32 v126, v126, v68
	v_sub_f32_e32 v125, v125, v68
	v_sub_f32_e32 v124, v124, v68
	v_sub_f32_e32 v123, v123, v68
	v_sub_f32_e32 v122, v122, v68
	v_sub_f32_e32 v121, v121, v68
	v_sub_f32_e32 v120, v120, v68
	v_sub_f32_e32 v119, v119, v68
	v_sub_f32_e32 v118, v118, v68
	v_sub_f32_e32 v117, v117, v68
	v_sub_f32_e32 v116, v116, v68
	v_sub_f32_e32 v115, v115, v68
	v_sub_f32_e32 v114, v114, v68
	v_sub_f32_e32 v113, v113, v68
	v_sub_f32_e32 v112, v112, v68
	v_xor_b32_e32 v68, 0x80000000, v229
	v_mov_b32_e32 v80, v68
	v_mov_b32_e32 v81, v68
	v_mov_b32_e32 v82, v68
	v_mov_b32_e32 v83, v68
	v_mov_b32_e32 v84, v68
	v_mov_b32_e32 v85, v68
	v_mov_b32_e32 v86, v68
	v_mov_b32_e32 v87, v68
	v_mov_b32_e32 v88, v68
	v_mov_b32_e32 v89, v68
	v_mov_b32_e32 v90, v68
	v_mov_b32_e32 v91, v68
	v_mov_b32_e32 v92, v68
	v_mov_b32_e32 v93, v68
	v_mov_b32_e32 v94, v68
	v_mov_b32_e32 v95, v68
	s_branch .LBB0_98
.LBB0_110:
	v_max_f32_e32 v68, v179, v179
	v_max_f32_e32 v68, 0, v68
	v_exp_f32_e64 v178, -v68
	v_add_f32_e32 v229, v229, v68
	v_pk_add_f32 v[128:129], v[128:129], v[68:69] op_sel_hi:[1,0] neg_lo:[0,1] neg_hi:[0,1]
	v_pk_add_f32 v[130:131], v[130:131], v[68:69] op_sel_hi:[1,0] neg_lo:[0,1] neg_hi:[0,1]
	v_pk_add_f32 v[132:133], v[132:133], v[68:69] op_sel_hi:[1,0] neg_lo:[0,1] neg_hi:[0,1]
	v_pk_add_f32 v[134:135], v[134:135], v[68:69] op_sel_hi:[1,0] neg_lo:[0,1] neg_hi:[0,1]
	v_pk_add_f32 v[136:137], v[136:137], v[68:69] op_sel_hi:[1,0] neg_lo:[0,1] neg_hi:[0,1]
	v_pk_add_f32 v[138:139], v[138:139], v[68:69] op_sel_hi:[1,0] neg_lo:[0,1] neg_hi:[0,1]
	v_pk_add_f32 v[140:141], v[140:141], v[68:69] op_sel_hi:[1,0] neg_lo:[0,1] neg_hi:[0,1]
	v_pk_add_f32 v[142:143], v[142:143], v[68:69] op_sel_hi:[1,0] neg_lo:[0,1] neg_hi:[0,1]
	v_sub_f32_e32 v111, v111, v68
	v_sub_f32_e32 v110, v110, v68
	v_sub_f32_e32 v109, v109, v68
	v_sub_f32_e32 v108, v108, v68
	v_sub_f32_e32 v107, v107, v68
	v_sub_f32_e32 v106, v106, v68
	v_sub_f32_e32 v105, v105, v68
	v_sub_f32_e32 v104, v104, v68
	v_sub_f32_e32 v103, v103, v68
	v_sub_f32_e32 v102, v102, v68
	v_sub_f32_e32 v101, v101, v68
	v_sub_f32_e32 v100, v100, v68
	v_sub_f32_e32 v99, v99, v68
	v_sub_f32_e32 v98, v98, v68
	v_sub_f32_e32 v97, v97, v68
	v_sub_f32_e32 v96, v96, v68
	v_xor_b32_e32 v68, 0x80000000, v229
	v_mov_b32_e32 v80, v68
	v_mov_b32_e32 v81, v68
	v_mov_b32_e32 v82, v68
	v_mov_b32_e32 v83, v68
	v_mov_b32_e32 v84, v68
	v_mov_b32_e32 v85, v68
	v_mov_b32_e32 v86, v68
	v_mov_b32_e32 v87, v68
	v_mov_b32_e32 v88, v68
	v_mov_b32_e32 v89, v68
	v_mov_b32_e32 v90, v68
	v_mov_b32_e32 v91, v68
	v_mov_b32_e32 v92, v68
	v_mov_b32_e32 v93, v68
	v_mov_b32_e32 v94, v68
	v_mov_b32_e32 v95, v68
	s_branch .LBB0_103
; #define SBAR() __builtin_amdgcn_sched_barrier(0)
; __device__ __forceinline__ void finishSM(f32x16& p0, f32x16& p1, float alpha, float& l_reg, bf16x8& pa0, bf16x8& pa1, bf16x8& pa2, bf16x8& pa3) {
;   for (int r = 0; r < 16; ++r) p1[r] = __builtin_amdgcn_exp2f(p1[r]);
;   float ps = 0; for (int r = 0; r < 16; ++r) ps += p0[r]; for (int r = 0; r < 16; ++r) ps += p1[r];
;   { auto rr = __builtin_amdgcn_permlane32_swap(__float_as_uint(ps), __float_as_uint(ps), false, false);
;     ps = __uint_as_float(rr[0]) + __uint_as_float(rr[1]); }
;   l_reg = l_reg * alpha + ps;
;     ...
;   PK4(p0, 0, pa0); PK4(p0, 8, pa1); PK4(p1, 0, pa2); PK4(p1, 8, pa3);
; __device__ __forceinline__ void attn_dense_body(const bf16* Qb, const bf16* __restrict__ Kh, const bf16* __restrict__ Vh,
;                                                 bf16* Ob, int seq, char* lds, const float* __restrict__ qg, const float* __restrict__ rope, int s0) {
;     ...
;   SBAR(); qkt(pB0, pB1, (bf16*)((char*)K_lds + SHM_K), qr, negm, r32, hi);
;   finishSM(pA0, pA1, alA, l_reg, pa0, pa1, pa2, pa3); SBAR();
;   pv_d0(o, vb0, pa0, pa1, pa2, pa3); partialSM<false>(pB0, pB1, m_reg, negm, alB);
.LBB0_111:
	s_waitcnt vmcnt(0)
	v_mov_b64_e32 v[64:65], v[80:81]
	v_mov_b64_e32 v[66:67], v[82:83]
	v_mov_b64_e32 v[68:69], v[84:85]
	v_mov_b64_e32 v[70:71], v[86:87]
	v_mov_b64_e32 v[72:73], v[88:89]
	v_mov_b64_e32 v[74:75], v[90:91]
	v_mov_b64_e32 v[76:77], v[92:93]
	v_mov_b64_e32 v[78:79], v[94:95]
	ds_read_b128 v[112:115], v216 offset:57344
	ds_read_b128 v[116:119], v216 offset:49152
	v_exp_f32_e32 v120, v104
	v_exp_f32_e32 v121, v105
	v_exp_f32_e32 v122, v106
	v_exp_f32_e32 v123, v107
	s_waitcnt lgkmcnt(0)
	v_mfma_f32_32x32x16_bf16 v[80:95], v[116:119], v[146:149], v[64:79]
	v_exp_f32_e32 v124, v108
	v_exp_f32_e32 v125, v109
	v_exp_f32_e32 v126, v110
	v_exp_f32_e32 v127, v111
	v_mfma_f32_32x32x16_bf16 v[64:79], v[112:115], v[146:149], v[64:79]
	ds_read_b128 v[112:115], v224 offset:57344
	ds_read_b128 v[116:119], v224 offset:49152
	s_waitcnt lgkmcnt(1)
	v_mfma_f32_32x32x16_bf16 v[64:79], v[112:115], v[150:153], v[64:79]
	s_waitcnt lgkmcnt(0)
	v_mfma_f32_32x32x16_bf16 v[80:95], v[116:119], v[150:153], v[80:95]
	ds_read_b128 v[112:115], v223 offset:57344
	ds_read_b128 v[116:119], v223 offset:49152
	s_waitcnt lgkmcnt(1)
	v_mfma_f32_32x32x16_bf16 v[64:79], v[112:115], v[154:157], v[64:79]
	s_waitcnt lgkmcnt(0)
	v_mfma_f32_32x32x16_bf16 v[80:95], v[116:119], v[154:157], v[80:95]
	ds_read_b128 v[112:115], v221 offset:57344
	ds_read_b128 v[116:119], v221 offset:49152
	s_waitcnt lgkmcnt(1)
	v_mfma_f32_32x32x16_bf16 v[64:79], v[112:115], v[158:161], v[64:79]
	s_waitcnt lgkmcnt(0)
	v_mfma_f32_32x32x16_bf16 v[80:95], v[116:119], v[158:161], v[80:95]
	ds_read_b128 v[112:115], v222 offset:57344
	ds_read_b128 v[116:119], v222 offset:49152
	s_waitcnt lgkmcnt(1)
	v_mfma_f32_32x32x16_bf16 v[64:79], v[112:115], v[162:165], v[64:79]
	s_waitcnt lgkmcnt(0)
	v_mfma_f32_32x32x16_bf16 v[80:95], v[116:119], v[162:165], v[80:95]
	ds_read_b128 v[112:115], v225 offset:57344
	ds_read_b128 v[116:119], v225 offset:49152
	s_waitcnt lgkmcnt(1)
	v_mfma_f32_32x32x16_bf16 v[64:79], v[112:115], v[166:169], v[64:79]
	s_waitcnt lgkmcnt(0)
	v_mfma_f32_32x32x16_bf16 v[80:95], v[116:119], v[166:169], v[80:95]
	ds_read_b128 v[112:115], v226 offset:57344
	ds_read_b128 v[116:119], v226 offset:49152
	s_waitcnt lgkmcnt(1)
	v_mfma_f32_32x32x16_bf16 v[64:79], v[112:115], v[170:173], v[64:79]
	s_waitcnt lgkmcnt(0)
	v_mfma_f32_32x32x16_bf16 v[80:95], v[116:119], v[170:173], v[80:95]
	ds_read_b128 v[112:115], v227 offset:57344
	ds_read_b128 v[116:119], v227 offset:49152
	s_waitcnt lgkmcnt(1)
	v_mfma_f32_32x32x16_bf16 v[64:79], v[112:115], v[174:177], v[64:79]
	v_exp_f32_e32 v112, v96
	v_add_f32_e32 v96, 0, v245
	v_add_f32_e32 v96, v247, v96
	v_add_f32_e32 v96, v179, v96
	v_add_f32_e32 v96, v246, v96
	v_add_f32_e32 v96, v180, v96
	v_add_f32_e32 v96, v244, v96
	v_add_f32_e32 v96, v181, v96
	v_add_f32_e32 v96, v243, v96
	v_add_f32_e32 v96, v240, v96
	v_add_f32_e32 v96, v242, v96
	v_add_f32_e32 v96, v239, v96
	v_add_f32_e32 v96, v241, v96
	v_add_f32_e32 v96, v236, v96
	v_exp_f32_e32 v113, v97
	v_add_f32_e32 v96, v238, v96
	v_exp_f32_e32 v114, v98
	v_add_f32_e32 v96, v235, v96
	v_exp_f32_e32 v115, v99
	v_add_f32_e32 v96, v237, v96
	s_waitcnt lgkmcnt(0)
	v_mfma_f32_32x32x16_bf16 v[80:95], v[116:119], v[174:177], v[80:95]
	v_exp_f32_e32 v116, v100
	v_add_f32_e32 v96, v112, v96
	v_exp_f32_e32 v117, v101
	v_add_f32_e32 v96, v113, v96
	v_exp_f32_e32 v118, v102
	v_add_f32_e32 v96, v114, v96
	v_exp_f32_e32 v119, v103
	v_add_f32_e32 v96, v115, v96
	v_add_f32_e32 v96, v116, v96
	v_add_f32_e32 v96, v117, v96
	v_add_f32_e32 v96, v118, v96
	v_add_f32_e32 v96, v119, v96
	v_add_f32_e32 v96, v120, v96
	v_add_f32_e32 v96, v121, v96
	v_add_f32_e32 v96, v122, v96
	v_add_f32_e32 v96, v123, v96
	v_add_f32_e32 v96, v124, v96
	v_add_f32_e32 v96, v125, v96
	v_add_f32_e32 v96, v126, v96
	v_add_f32_e32 v100, v127, v96
	v_mov_b32_e32 v101, v100
	v_cvt_pk_bf16_f32 v96, v245, v247
	v_cvt_pk_bf16_f32 v97, v179, v246
	v_cvt_pk_bf16_f32 v98, v180, v244
	v_cvt_pk_bf16_f32 v99, v181, v243
	s_nop 1
	v_permlane32_swap_b32_e32 v100, v101
	v_permlane32_swap_b32_e32 v96, v98
	v_permlane32_swap_b32_e32 v97, v99
	v_cvt_pk_bf16_f32 v102, v240, v242
	v_cvt_pk_bf16_f32 v103, v239, v241
	v_cvt_pk_bf16_f32 v104, v236, v238
	v_cvt_pk_bf16_f32 v105, v235, v237
	v_cvt_pk_bf16_f32 v106, v112, v113
	v_cvt_pk_bf16_f32 v107, v114, v115
	v_cvt_pk_bf16_f32 v108, v116, v117
	v_cvt_pk_bf16_f32 v109, v118, v119
	v_cvt_pk_bf16_f32 v110, v120, v121
	v_cvt_pk_bf16_f32 v111, v122, v123
	v_cvt_pk_bf16_f32 v112, v124, v125
	v_cvt_pk_bf16_f32 v113, v126, v127
	s_nop 0
	v_permlane32_swap_b32_e32 v102, v104
	v_permlane32_swap_b32_e32 v103, v105
	v_permlane32_swap_b32_e32 v106, v108
	v_permlane32_swap_b32_e32 v107, v109
	v_permlane32_swap_b32_e32 v110, v112
	v_permlane32_swap_b32_e32 v111, v113
	ds_read_b64_tr_b16 v[114:115], v213 offset:0
	ds_read_b64_tr_b16 v[116:117], v213 offset:0x800
	ds_read_b64_tr_b16 v[118:119], v213 offset:0x1000
	ds_read_b64_tr_b16 v[120:121], v213 offset:0x1800
	ds_read_b64_tr_b16 v[122:123], v213 offset:0x2000
	ds_read_b64_tr_b16 v[124:125], v213 offset:0x2800
	ds_read_b64_tr_b16 v[126:127], v213 offset:0x3000
	ds_read_b64_tr_b16 v[128:129], v213 offset:0x3800
	s_waitcnt lgkmcnt(0)
; #define SBAR() __builtin_amdgcn_sched_barrier(0)
; template <int D0> __device__ __forceinline__ void pv_one(f32x16& od, int vb, bf16x8 pa0, bf16x8 pa1, bf16x8 pa2, bf16x8 pa3) {
;   const s16x4 l0 = tr_read<v_rd_off(D0, 0, 0)>(vb), h0 = tr_read<v_rd_off(D0, 0, 1)>(vb), l1 = tr_read<v_rd_off(D0, 1, 0)>(vb), h1 = tr_read<v_rd_off(D0, 1, 1)>(vb);
;   const s16x4 l2 = tr_read<v_rd_off(D0, 2, 0)>(vb), h2 = tr_read<v_rd_off(D0, 2, 1)>(vb), l3 = tr_read<v_rd_off(D0, 3, 0)>(vb), h3 = tr_read<v_rd_off(D0, 3, 1)>(vb);
;   asm volatile("s_waitcnt lgkmcnt(0)" ::: "memory"); SBAR();
;     ...
;   od = __builtin_amdgcn_mfma_f32_32x32x16_bf16(pa0, PK(l0, h0), od, 0, 0, 0);
;   od = __builtin_amdgcn_mfma_f32_32x32x16_bf16(pa1, PK(l1, h1), od, 0, 0, 0);
;   od = __builtin_amdgcn_mfma_f32_32x32x16_bf16(pa2, PK(l2, h2), od, 0, 0, 0);
;   od = __builtin_amdgcn_mfma_f32_32x32x16_bf16(pa3, PK(l3, h3), od, 0, 0, 0);
;     ...
; }
; __device__ __forceinline__ void pv_d0(f32x16* o, int vb, bf16x8 pa0, bf16x8 pa1, bf16x8 pa2, bf16x8 pa3) {
;   pv_one<0>(o[0], vb, pa0, pa1, pa2, pa3); pv_one<1>(o[1], vb, pa0, pa1, pa2, pa3); pv_one<2>(o[2], vb, pa0, pa1, pa2, pa3); pv_one<3>(o[3], vb, pa0, pa1, pa2, pa3);
; __device__ __forceinline__ void attn_dense_body(const bf16* Qb, const bf16* __restrict__ Kh, const bf16* __restrict__ Vh,
;                                                 bf16* Ob, int seq, char* lds, const float* __restrict__ qg, const float* __restrict__ rope, int s0) {
;     ...
;   pv_d0(o, vb0, pa0, pa1, pa2, pa3); partialSM<false>(pB0, pB1, m_reg, negm, alB);
	s_nop 0
	v_mfma_f32_32x32x16_bf16 v[0:15], v[96:99], v[114:117], v[0:15]
	ds_read_b64_tr_b16 v[114:115], v213 offset:0x200
	ds_read_b64_tr_b16 v[116:117], v213 offset:0xa00
	v_mfma_f32_32x32x16_bf16 v[0:15], v[102:105], v[118:121], v[0:15]
	ds_read_b64_tr_b16 v[118:119], v213 offset:0x1200
	ds_read_b64_tr_b16 v[120:121], v213 offset:0x1a00
	v_mfma_f32_32x32x16_bf16 v[0:15], v[106:109], v[122:125], v[0:15]
	ds_read_b64_tr_b16 v[122:123], v213 offset:0x2200
	ds_read_b64_tr_b16 v[124:125], v213 offset:0x2a00
	v_mfma_f32_32x32x16_bf16 v[0:15], v[110:113], v[126:129], v[0:15]
	ds_read_b64_tr_b16 v[126:127], v213 offset:0x3200
	ds_read_b64_tr_b16 v[128:129], v213 offset:0x3a00
	s_waitcnt lgkmcnt(0)
	v_mfma_f32_32x32x16_bf16 v[32:47], v[96:99], v[114:117], v[32:47]
	ds_read_b64_tr_b16 v[114:115], v213 offset:0x400
	ds_read_b64_tr_b16 v[116:117], v213 offset:0xc00
	v_mfma_f32_32x32x16_bf16 v[32:47], v[102:105], v[118:121], v[32:47]
	ds_read_b64_tr_b16 v[118:119], v213 offset:0x1400
	ds_read_b64_tr_b16 v[120:121], v213 offset:0x1c00
	v_mfma_f32_32x32x16_bf16 v[32:47], v[106:109], v[122:125], v[32:47]
	ds_read_b64_tr_b16 v[122:123], v213 offset:0x2400
	ds_read_b64_tr_b16 v[124:125], v213 offset:0x2c00
	v_mfma_f32_32x32x16_bf16 v[32:47], v[110:113], v[126:129], v[32:47]
	ds_read_b64_tr_b16 v[126:127], v213 offset:0x3400
	ds_read_b64_tr_b16 v[128:129], v213 offset:0x3c00
	s_waitcnt lgkmcnt(0)
	v_mfma_f32_32x32x16_bf16 v[16:31], v[96:99], v[114:117], v[16:31]
	ds_read_b64_tr_b16 v[114:115], v213 offset:0x600
	ds_read_b64_tr_b16 v[116:117], v213 offset:0xe00
	v_mfma_f32_32x32x16_bf16 v[16:31], v[102:105], v[118:121], v[16:31]
	ds_read_b64_tr_b16 v[118:119], v213 offset:0x1600
	ds_read_b64_tr_b16 v[120:121], v213 offset:0x1e00
	v_mfma_f32_32x32x16_bf16 v[16:31], v[106:109], v[122:125], v[16:31]
	ds_read_b64_tr_b16 v[122:123], v213 offset:0x2600
	ds_read_b64_tr_b16 v[124:125], v213 offset:0x2e00
	v_mfma_f32_32x32x16_bf16 v[16:31], v[110:113], v[126:129], v[16:31]
	ds_read_b64_tr_b16 v[126:127], v213 offset:0x3600
	ds_read_b64_tr_b16 v[128:129], v213 offset:0x3e00
	s_waitcnt lgkmcnt(0)
	v_mfma_f32_32x32x16_bf16 v[48:63], v[96:99], v[114:117], v[48:63]
	v_max_f32_e32 v96, v81, v81
	v_max_f32_e32 v97, v80, v80
	v_max_f32_e32 v96, v97, v96
	v_max3_f32 v96, v96, v82, v83
	v_max3_f32 v96, v96, v84, v85
	v_max3_f32 v96, v96, v86, v87
	v_max3_f32 v96, v96, v88, v89
	v_mfma_f32_32x32x16_bf16 v[48:63], v[102:105], v[118:121], v[48:63]
	v_max3_f32 v96, v96, v90, v91
	v_max3_f32 v96, v96, v92, v93
	v_max3_f32 v96, v96, v94, v95
	v_max3_f32 v96, v96, v64, v65
	v_max3_f32 v96, v96, v66, v67
	v_max3_f32 v96, v96, v68, v69
	v_max3_f32 v96, v96, v70, v71
	v_mfma_f32_32x32x16_bf16 v[48:63], v[106:109], v[122:125], v[48:63]
	v_max3_f32 v96, v96, v72, v73
	v_max3_f32 v96, v96, v74, v75
	v_max3_f32 v96, v96, v76, v77
	v_max3_f32 v96, v96, v78, v79
	v_mov_b32_e32 v97, v96
	s_nop 1
	v_permlane32_swap_b32_e32 v96, v97
	v_mfma_f32_32x32x16_bf16 v[48:63], v[110:113], v[126:129], v[48:63]
	v_max_f32_e32 v97, v97, v97
	v_max_f32_e32 v96, v96, v96
	v_max_f32_e32 v97, v96, v97
	v_cmp_ge_f32_e32 vcc, s5, v97
	s_cmp_eq_u64 vcc, exec
	v_mov_b32_e32 v96, 1.0
	s_cbranch_scc0 .LBB0_118

; __global__ void __launch_bounds__(NTHR, 2) mega_fwd(Args a0) {
	.amdhsa_kernel _Z8mega_fwd4Args
		.amdhsa_group_segment_fixed_size 0
		.amdhsa_private_segment_fixed_size 0
		.amdhsa_kernarg_size 464
		.amdhsa_user_sgpr_count 2
		.amdhsa_user_sgpr_dispatch_ptr 0
		.amdhsa_user_sgpr_queue_ptr 0
		.amdhsa_user_sgpr_kernarg_segment_ptr 1
		.amdhsa_user_sgpr_dispatch_id 0
		.amdhsa_user_sgpr_kernarg_preload_length 0
		.amdhsa_user_sgpr_kernarg_preload_offset 0
		.amdhsa_user_sgpr_private_segment_size 0
		.amdhsa_uses_dynamic_stack 0
		.amdhsa_enable_private_segment 0
		.amdhsa_system_sgpr_workgroup_id_x 1
		.amdhsa_system_sgpr_workgroup_id_y 0
		.amdhsa_system_sgpr_workgroup_id_z 0
		.amdhsa_system_sgpr_workgroup_info 0
		.amdhsa_system_vgpr_workitem_id 2
		.amdhsa_next_free_vgpr 256
		.amdhsa_next_free_sgpr 100
		.amdhsa_accum_offset 256
		.amdhsa_reserve_vcc 1
		.amdhsa_float_round_mode_32 0
		.amdhsa_float_round_mode_16_64 0
		.amdhsa_float_denorm_mode_32 3
		.amdhsa_float_denorm_mode_16_64 3
		.amdhsa_dx10_clamp 1
		.amdhsa_ieee_mode 1
		.amdhsa_fp16_overflow 0
		.amdhsa_tg_split 0
		.amdhsa_exception_fp_ieee_invalid_op 0
		.amdhsa_exception_fp_denorm_src 0
		.amdhsa_exception_fp_ieee_div_zero 0
		.amdhsa_exception_fp_ieee_overflow 0
		.amdhsa_exception_fp_ieee_underflow 0
		.amdhsa_exception_fp_ieee_inexact 0
		.amdhsa_exception_int_div_zero 0
	.end_amdhsa_kernel

; __global__ void __launch_bounds__(NTHR, 2) mega_fwd(Args a0) {
amdhsa.kernels:
  - .agpr_count:     0
    .args:
      - .offset:         0
        .size:           208
        .value_kind:     by_value
      - .offset:         208
        .size:           4
        .value_kind:     hidden_block_count_x
      - .offset:         212
        .size:           4
        .value_kind:     hidden_block_count_y
      - .offset:         216
        .size:           4
        .value_kind:     hidden_block_count_z
      - .offset:         220
        .size:           2
        .value_kind:     hidden_group_size_x
      - .offset:         222
        .size:           2
        .value_kind:     hidden_group_size_y
      - .offset:         224
        .size:           2
        .value_kind:     hidden_group_size_z
      - .offset:         226
        .size:           2
        .value_kind:     hidden_remainder_x
      - .offset:         228
        .size:           2
        .value_kind:     hidden_remainder_y
      - .offset:         230
        .size:           2
        .value_kind:     hidden_remainder_z
      - .offset:         248
        .size:           8
        .value_kind:     hidden_global_offset_x
      - .offset:         256
        .size:           8
        .value_kind:     hidden_global_offset_y
      - .offset:         264
        .size:           8
        .value_kind:     hidden_global_offset_z
      - .offset:         272
        .size:           2
        .value_kind:     hidden_grid_dims
      - .offset:         296
        .size:           8
        .value_kind:     hidden_multigrid_sync_arg
      - .offset:         328
        .size:           4
        .value_kind:     hidden_dynamic_lds_size
    .group_segment_fixed_size: 0
    .kernarg_segment_align: 8
    .kernarg_segment_size: 464
    .language:       OpenCL C
    .language_version:
      - 2
      - 0
    .max_flat_workgroup_size: 512
    .name:           _Z8mega_fwd4Args
    .private_segment_fixed_size: 0
    .sgpr_count:     106
    .sgpr_spill_count: 200
    .symbol:         _Z8mega_fwd4Args.kd
    .uniform_work_group_size: 1
    .uses_dynamic_stack: false
    .vgpr_count:     256
    .vgpr_spill_count: 0
    .wavefront_size: 64
